# v33 plus removal of the redundant mid-burst s_setprio 0/1 pairs inside MMA segments
# baseline (speedup 1.0000x reference)
.LBB0_163:
	s_or_b32 s14, s18, 1
	s_lshl_b64 s[20:21], s[14:15], 7
	s_add_u32 s19, s12, s20
	s_addc_u32 s40, s13, s21
	s_add_i32 s14, s18, 2
	s_lshl_b64 s[20:21], s[14:15], 7
	s_cmp_lg_u32 s18, s25
	s_cselect_b32 s42, s20, 0
	s_cselect_b32 s41, s21, 0
	s_add_u32 s20, s12, s42
	s_addc_u32 s21, s13, s41
	s_add_u32 s18, s19, 0x40000
	s_addc_u32 s19, s40, 0
	s_mov_b32 m0, s29
	v_lshl_add_u64 v[144:145], s[18:19], 0, v[136:137]
	global_load_lds_dwordx4 v[144:145], off
	v_lshl_add_u64 v[144:145], s[18:19], 0, v[132:133]
	s_mov_b32 m0, s30
	s_add_u32 s18, s8, s42
	global_load_lds_dwordx4 v[144:145], off
	s_addc_u32 s19, s9, s41
	ds_read_b128 v[144:147], v139
	ds_read_b128 v[148:151], v139 offset:1024
	ds_read_b128 v[152:155], v139 offset:2048
	ds_read_b128 v[156:159], v139 offset:3072
	ds_read_b128 v[160:163], v140
	ds_read_b128 v[164:167], v140 offset:1024
	ds_read_b128 v[168:171], v140 offset:2048
	ds_read_b128 v[172:175], v140 offset:3072
	ds_read_b128 v[176:179], v141
	ds_read_b128 v[180:183], v141 offset:1024
	ds_read_b128 v[184:187], v141 offset:2048
	ds_read_b128 v[188:191], v141 offset:3072
	ds_read_b128 v[192:195], v141 offset:4096
	ds_read_b128 v[196:199], v141 offset:5120
	ds_read_b128 v[200:203], v141 offset:6144
	ds_read_b128 v[204:207], v141 offset:7168
	s_waitcnt vmcnt(8)
	s_waitcnt lgkmcnt(0)
	s_barrier
	s_setprio 1
	s_waitcnt lgkmcnt(0)
	v_mfma_f32_16x16x32_bf16 v[126:129], v[144:147], v[176:179], v[126:129]
	v_mfma_f32_16x16x32_bf16 v[122:125], v[152:155], v[176:179], v[122:125]
	v_mfma_f32_16x16x32_bf16 v[118:121], v[144:147], v[184:187], v[118:121]
	v_mfma_f32_16x16x32_bf16 v[114:117], v[152:155], v[184:187], v[114:117]
	v_mfma_f32_16x16x32_bf16 v[102:105], v[144:147], v[192:195], v[102:105]
	v_mfma_f32_16x16x32_bf16 v[98:101], v[152:155], v[192:195], v[98:101]
	v_mfma_f32_16x16x32_bf16 v[86:89], v[144:147], v[200:203], v[86:89]
	v_mfma_f32_16x16x32_bf16 v[82:85], v[152:155], v[200:203], v[82:85]
	v_mfma_f32_16x16x32_bf16 v[126:129], v[148:151], v[180:183], v[126:129]
	v_mfma_f32_16x16x32_bf16 v[122:125], v[156:159], v[180:183], v[122:125]
	v_mfma_f32_16x16x32_bf16 v[118:121], v[148:151], v[188:191], v[118:121]
	v_mfma_f32_16x16x32_bf16 v[114:117], v[156:159], v[188:191], v[114:117]
	v_mfma_f32_16x16x32_bf16 v[102:105], v[148:151], v[196:199], v[102:105]
	v_mfma_f32_16x16x32_bf16 v[98:101], v[156:159], v[196:199], v[98:101]
	v_mfma_f32_16x16x32_bf16 v[86:89], v[148:151], v[204:207], v[86:89]
	v_mfma_f32_16x16x32_bf16 v[82:85], v[156:159], v[204:207], v[82:85]
	v_mfma_f32_16x16x32_bf16 v[110:113], v[160:163], v[176:179], v[110:113]
	v_mfma_f32_16x16x32_bf16 v[106:109], v[168:171], v[176:179], v[106:109]
	v_mfma_f32_16x16x32_bf16 v[94:97], v[160:163], v[184:187], v[94:97]
	v_mfma_f32_16x16x32_bf16 v[90:93], v[168:171], v[184:187], v[90:93]
	v_mfma_f32_16x16x32_bf16 v[78:81], v[160:163], v[192:195], v[78:81]
	v_mfma_f32_16x16x32_bf16 v[74:77], v[168:171], v[192:195], v[74:77]
	v_mfma_f32_16x16x32_bf16 v[70:73], v[160:163], v[200:203], v[70:73]
	v_mfma_f32_16x16x32_bf16 v[66:69], v[168:171], v[200:203], v[66:69]
	v_mfma_f32_16x16x32_bf16 v[110:113], v[164:167], v[180:183], v[110:113]
	v_mfma_f32_16x16x32_bf16 v[106:109], v[172:175], v[180:183], v[106:109]
	v_mfma_f32_16x16x32_bf16 v[94:97], v[164:167], v[188:191], v[94:97]
	v_mfma_f32_16x16x32_bf16 v[90:93], v[172:175], v[188:191], v[90:93]
	v_mfma_f32_16x16x32_bf16 v[78:81], v[164:167], v[196:199], v[78:81]
	v_mfma_f32_16x16x32_bf16 v[74:77], v[172:175], v[196:199], v[74:77]
	v_mfma_f32_16x16x32_bf16 v[70:73], v[164:167], v[204:207], v[70:73]
	v_mfma_f32_16x16x32_bf16 v[66:69], v[172:175], v[204:207], v[66:69]
	s_setprio 0
	s_barrier
	s_mov_b32 m0, s31
	v_lshl_add_u64 v[208:209], s[18:19], 0, v[134:135]
	s_add_u32 s40, s18, 0x40000
	global_load_lds_dwordx4 v[208:209], off
	v_lshl_add_u64 v[210:211], s[18:19], 0, v[130:131]
	s_mov_b32 m0, s33
	s_addc_u32 s41, s19, 0
	global_load_lds_dwordx4 v[210:211], off
	v_lshl_add_u64 v[176:177], s[40:41], 0, v[134:135]
	s_mov_b32 m0, s34
	v_lshl_add_u64 v[212:213], s[20:21], 0, v[136:137]
	global_load_lds_dwordx4 v[176:177], off
	v_lshl_add_u64 v[176:177], s[40:41], 0, v[130:131]
	s_mov_b32 m0, s35
	v_lshl_add_u64 v[214:215], s[20:21], 0, v[132:133]
	global_load_lds_dwordx4 v[176:177], off
	s_mov_b32 m0, s6
	s_nop 0
	global_load_lds_dwordx4 v[212:213], off
	s_mov_b32 m0, s7
	s_nop 0
	global_load_lds_dwordx4 v[214:215], off
	ds_read_b128 v[176:179], v141 offset:16384
	ds_read_b128 v[180:183], v141 offset:17408
	ds_read_b128 v[184:187], v141 offset:18432
	ds_read_b128 v[188:191], v141 offset:19456
	ds_read_b128 v[192:195], v141 offset:20480
	ds_read_b128 v[196:199], v141 offset:21504
	ds_read_b128 v[200:203], v141 offset:22528
	ds_read_b128 v[204:207], v141 offset:23552
	s_waitcnt vmcnt(8)
	s_waitcnt lgkmcnt(0)
	s_barrier
	s_setprio 1
	s_waitcnt lgkmcnt(0)
	v_mfma_f32_16x16x32_bf16 v[62:65], v[144:147], v[176:179], v[62:65]
	v_mfma_f32_16x16x32_bf16 v[58:61], v[152:155], v[176:179], v[58:61]
	v_mfma_f32_16x16x32_bf16 v[54:57], v[144:147], v[184:187], v[54:57]
	v_mfma_f32_16x16x32_bf16 v[50:53], v[152:155], v[184:187], v[50:53]
	v_mfma_f32_16x16x32_bf16 v[38:41], v[144:147], v[192:195], v[38:41]
	v_mfma_f32_16x16x32_bf16 v[34:37], v[152:155], v[192:195], v[34:37]
	v_mfma_f32_16x16x32_bf16 v[22:25], v[144:147], v[200:203], v[22:25]
	v_mfma_f32_16x16x32_bf16 v[18:21], v[152:155], v[200:203], v[18:21]
	v_mfma_f32_16x16x32_bf16 v[62:65], v[148:151], v[180:183], v[62:65]
	v_mfma_f32_16x16x32_bf16 v[58:61], v[156:159], v[180:183], v[58:61]
	v_mfma_f32_16x16x32_bf16 v[54:57], v[148:151], v[188:191], v[54:57]
	v_mfma_f32_16x16x32_bf16 v[50:53], v[156:159], v[188:191], v[50:53]
	v_mfma_f32_16x16x32_bf16 v[38:41], v[148:151], v[196:199], v[38:41]
	v_mfma_f32_16x16x32_bf16 v[34:37], v[156:159], v[196:199], v[34:37]
	v_mfma_f32_16x16x32_bf16 v[22:25], v[148:151], v[204:207], v[22:25]
	v_mfma_f32_16x16x32_bf16 v[18:21], v[156:159], v[204:207], v[18:21]
	v_mfma_f32_16x16x32_bf16 v[46:49], v[160:163], v[176:179], v[46:49]
	v_mfma_f32_16x16x32_bf16 v[42:45], v[168:171], v[176:179], v[42:45]
	v_mfma_f32_16x16x32_bf16 v[30:33], v[160:163], v[184:187], v[30:33]
	v_mfma_f32_16x16x32_bf16 v[26:29], v[168:171], v[184:187], v[26:29]
	v_mfma_f32_16x16x32_bf16 v[14:17], v[160:163], v[192:195], v[14:17]
	v_mfma_f32_16x16x32_bf16 v[10:13], v[168:171], v[192:195], v[10:13]
	v_mfma_f32_16x16x32_bf16 v[6:9], v[160:163], v[200:203], v[6:9]
	v_mfma_f32_16x16x32_bf16 v[2:5], v[168:171], v[200:203], v[2:5]
	v_mfma_f32_16x16x32_bf16 v[46:49], v[164:167], v[180:183], v[46:49]
	v_mfma_f32_16x16x32_bf16 v[42:45], v[172:175], v[180:183], v[42:45]
	v_mfma_f32_16x16x32_bf16 v[30:33], v[164:167], v[188:191], v[30:33]
	v_mfma_f32_16x16x32_bf16 v[26:29], v[172:175], v[188:191], v[26:29]
	v_mfma_f32_16x16x32_bf16 v[14:17], v[164:167], v[196:199], v[14:17]
	v_mfma_f32_16x16x32_bf16 v[10:13], v[172:175], v[196:199], v[10:13]
	v_mfma_f32_16x16x32_bf16 v[6:9], v[164:167], v[204:207], v[6:9]
	v_mfma_f32_16x16x32_bf16 v[2:5], v[172:175], v[204:207], v[2:5]
	s_setprio 0
	s_barrier
	s_add_u32 s20, s20, 0x40000
	s_addc_u32 s21, s21, 0
	s_mov_b32 m0, s22
	v_lshl_add_u64 v[144:145], s[20:21], 0, v[136:137]
	global_load_lds_dwordx4 v[144:145], off
	v_lshl_add_u64 v[144:145], s[20:21], 0, v[132:133]
	s_mov_b32 m0, s23
	s_nop 0
	global_load_lds_dwordx4 v[144:145], off
	ds_read_b128 v[144:147], v142
	ds_read_b128 v[148:151], v142 offset:1024
	ds_read_b128 v[152:155], v142 offset:2048
	ds_read_b128 v[156:159], v142 offset:3072
	ds_read_b128 v[160:163], v143
	ds_read_b128 v[164:167], v143 offset:1024
	ds_read_b128 v[168:171], v143 offset:2048
	ds_read_b128 v[172:175], v143 offset:3072
	ds_read_b128 v[176:179], v141 offset:32768
	ds_read_b128 v[180:183], v141 offset:33792
	ds_read_b128 v[184:187], v141 offset:34816
	ds_read_b128 v[188:191], v141 offset:35840
	ds_read_b128 v[192:195], v141 offset:36864
	ds_read_b128 v[196:199], v141 offset:37888
	ds_read_b128 v[200:203], v141 offset:38912
	ds_read_b128 v[204:207], v141 offset:39936
	s_waitcnt vmcnt(8)
	s_waitcnt lgkmcnt(0)
	s_barrier
	s_setprio 1
	s_waitcnt lgkmcnt(0)
	v_mfma_f32_16x16x32_bf16 v[126:129], v[144:147], v[176:179], v[126:129]
	v_mfma_f32_16x16x32_bf16 v[122:125], v[152:155], v[176:179], v[122:125]
	v_mfma_f32_16x16x32_bf16 v[118:121], v[144:147], v[184:187], v[118:121]
	v_mfma_f32_16x16x32_bf16 v[114:117], v[152:155], v[184:187], v[114:117]
	v_mfma_f32_16x16x32_bf16 v[102:105], v[144:147], v[192:195], v[102:105]
	v_mfma_f32_16x16x32_bf16 v[98:101], v[152:155], v[192:195], v[98:101]
	v_mfma_f32_16x16x32_bf16 v[86:89], v[144:147], v[200:203], v[86:89]
	v_mfma_f32_16x16x32_bf16 v[82:85], v[152:155], v[200:203], v[82:85]
	v_mfma_f32_16x16x32_bf16 v[126:129], v[148:151], v[180:183], v[126:129]
	v_mfma_f32_16x16x32_bf16 v[122:125], v[156:159], v[180:183], v[122:125]
	v_mfma_f32_16x16x32_bf16 v[118:121], v[148:151], v[188:191], v[118:121]
	v_mfma_f32_16x16x32_bf16 v[114:117], v[156:159], v[188:191], v[114:117]
	v_mfma_f32_16x16x32_bf16 v[102:105], v[148:151], v[196:199], v[102:105]
	v_mfma_f32_16x16x32_bf16 v[98:101], v[156:159], v[196:199], v[98:101]
	v_mfma_f32_16x16x32_bf16 v[86:89], v[148:151], v[204:207], v[86:89]
	v_mfma_f32_16x16x32_bf16 v[82:85], v[156:159], v[204:207], v[82:85]
	v_mfma_f32_16x16x32_bf16 v[110:113], v[160:163], v[176:179], v[110:113]
	v_mfma_f32_16x16x32_bf16 v[106:109], v[168:171], v[176:179], v[106:109]
	v_mfma_f32_16x16x32_bf16 v[94:97], v[160:163], v[184:187], v[94:97]
	v_mfma_f32_16x16x32_bf16 v[90:93], v[168:171], v[184:187], v[90:93]
	v_mfma_f32_16x16x32_bf16 v[78:81], v[160:163], v[192:195], v[78:81]
	v_mfma_f32_16x16x32_bf16 v[74:77], v[168:171], v[192:195], v[74:77]
	v_mfma_f32_16x16x32_bf16 v[70:73], v[160:163], v[200:203], v[70:73]
	v_mfma_f32_16x16x32_bf16 v[66:69], v[168:171], v[200:203], v[66:69]
	v_mfma_f32_16x16x32_bf16 v[110:113], v[164:167], v[180:183], v[110:113]
	v_mfma_f32_16x16x32_bf16 v[106:109], v[172:175], v[180:183], v[106:109]
	v_mfma_f32_16x16x32_bf16 v[94:97], v[164:167], v[188:191], v[94:97]
	v_mfma_f32_16x16x32_bf16 v[90:93], v[172:175], v[188:191], v[90:93]
	v_mfma_f32_16x16x32_bf16 v[78:81], v[164:167], v[196:199], v[78:81]
	v_mfma_f32_16x16x32_bf16 v[74:77], v[172:175], v[196:199], v[74:77]
	v_mfma_f32_16x16x32_bf16 v[70:73], v[164:167], v[204:207], v[70:73]
	v_mfma_f32_16x16x32_bf16 v[66:69], v[172:175], v[204:207], v[66:69]
	s_setprio 0
	s_barrier
	s_mov_b32 m0, s36
	v_lshl_add_u64 v[176:177], v[208:209], 0, s[16:17]
	s_add_u32 s18, s18, 0x40080
	global_load_lds_dwordx4 v[176:177], off
	v_lshl_add_u64 v[176:177], v[210:211], 0, s[16:17]
	s_mov_b32 m0, s37
	s_addc_u32 s19, s19, 0
	global_load_lds_dwordx4 v[176:177], off
	v_lshl_add_u64 v[176:177], s[18:19], 0, v[134:135]
	s_mov_b32 m0, s38
	s_nop 0
	global_load_lds_dwordx4 v[176:177], off
	v_lshl_add_u64 v[176:177], s[18:19], 0, v[130:131]
	s_mov_b32 m0, s39
	s_nop 0
	global_load_lds_dwordx4 v[176:177], off
	v_lshl_add_u64 v[176:177], v[212:213], 0, s[16:17]
	s_mov_b32 m0, s27
	s_nop 0
	global_load_lds_dwordx4 v[176:177], off
	v_lshl_add_u64 v[176:177], v[214:215], 0, s[16:17]
	s_mov_b32 m0, s28
	s_nop 0
	global_load_lds_dwordx4 v[176:177], off
	ds_read_b128 v[176:179], v141 offset:49152
	ds_read_b128 v[180:183], v141 offset:50176
	ds_read_b128 v[184:187], v141 offset:51200
	ds_read_b128 v[188:191], v141 offset:52224
	ds_read_b128 v[192:195], v141 offset:53248
	ds_read_b128 v[196:199], v141 offset:54272
	ds_read_b128 v[200:203], v141 offset:55296
	ds_read_b128 v[204:207], v141 offset:56320
	s_waitcnt vmcnt(8)
	s_waitcnt lgkmcnt(0)
	s_barrier
	s_setprio 1
	s_waitcnt lgkmcnt(0)
	v_mfma_f32_16x16x32_bf16 v[62:65], v[144:147], v[176:179], v[62:65]
	v_mfma_f32_16x16x32_bf16 v[58:61], v[152:155], v[176:179], v[58:61]
	v_mfma_f32_16x16x32_bf16 v[54:57], v[144:147], v[184:187], v[54:57]
	v_mfma_f32_16x16x32_bf16 v[50:53], v[152:155], v[184:187], v[50:53]
	v_mfma_f32_16x16x32_bf16 v[38:41], v[144:147], v[192:195], v[38:41]
	v_mfma_f32_16x16x32_bf16 v[34:37], v[152:155], v[192:195], v[34:37]
	v_mfma_f32_16x16x32_bf16 v[22:25], v[144:147], v[200:203], v[22:25]
	v_mfma_f32_16x16x32_bf16 v[18:21], v[152:155], v[200:203], v[18:21]
	v_mfma_f32_16x16x32_bf16 v[62:65], v[148:151], v[180:183], v[62:65]
	v_mfma_f32_16x16x32_bf16 v[58:61], v[156:159], v[180:183], v[58:61]
	v_mfma_f32_16x16x32_bf16 v[54:57], v[148:151], v[188:191], v[54:57]
	v_mfma_f32_16x16x32_bf16 v[50:53], v[156:159], v[188:191], v[50:53]
	v_mfma_f32_16x16x32_bf16 v[38:41], v[148:151], v[196:199], v[38:41]
	v_mfma_f32_16x16x32_bf16 v[34:37], v[156:159], v[196:199], v[34:37]
	v_mfma_f32_16x16x32_bf16 v[22:25], v[148:151], v[204:207], v[22:25]
	v_mfma_f32_16x16x32_bf16 v[18:21], v[156:159], v[204:207], v[18:21]
	v_mfma_f32_16x16x32_bf16 v[46:49], v[160:163], v[176:179], v[46:49]
	v_mfma_f32_16x16x32_bf16 v[42:45], v[168:171], v[176:179], v[42:45]
	v_mfma_f32_16x16x32_bf16 v[30:33], v[160:163], v[184:187], v[30:33]
	v_mfma_f32_16x16x32_bf16 v[26:29], v[168:171], v[184:187], v[26:29]
	v_mfma_f32_16x16x32_bf16 v[14:17], v[160:163], v[192:195], v[14:17]
	v_mfma_f32_16x16x32_bf16 v[10:13], v[168:171], v[192:195], v[10:13]
	v_mfma_f32_16x16x32_bf16 v[6:9], v[160:163], v[200:203], v[6:9]
	v_mfma_f32_16x16x32_bf16 v[2:5], v[168:171], v[200:203], v[2:5]
	v_mfma_f32_16x16x32_bf16 v[46:49], v[164:167], v[180:183], v[46:49]
	v_mfma_f32_16x16x32_bf16 v[42:45], v[172:175], v[180:183], v[42:45]
	v_mfma_f32_16x16x32_bf16 v[30:33], v[164:167], v[188:191], v[30:33]
	v_mfma_f32_16x16x32_bf16 v[26:29], v[172:175], v[188:191], v[26:29]
	v_mfma_f32_16x16x32_bf16 v[14:17], v[164:167], v[196:199], v[14:17]
	v_mfma_f32_16x16x32_bf16 v[10:13], v[172:175], v[196:199], v[10:13]
	v_mfma_f32_16x16x32_bf16 v[6:9], v[164:167], v[204:207], v[6:9]
	v_mfma_f32_16x16x32_bf16 v[2:5], v[172:175], v[204:207], v[2:5]
	s_setprio 0
	s_barrier
	s_cmp_ge_u32 s14, s24
	s_mov_b32 s18, s14
	s_cbranch_scc0 .LBB0_163
	s_lshl_b64 s[6:7], s[10:11], 23
	v_lshl_or_b32 v130, s3, 8, v138
	s_add_u32 s6, s94, s6
	v_or_b32_e32 v131, s26, v130
	s_addc_u32 s7, s95, s7
	v_lshl_add_u32 v130, s5, 8, v1
	v_lshlrev_b32_e32 v132, 1, v131
	v_mov_b32_e32 v133, 0
	v_lshl_add_u64 v[132:133], s[6:7], 0, v[132:133]
	s_mov_b64 s[6:7], 0x5400800
	v_ashrrev_i32_e32 v131, 31, v130
	v_lshl_add_u64 v[132:133], v[132:133], 0, s[6:7]
	v_lshlrev_b64 v[134:135], 12, v[130:131]
	v_lshl_add_u64 v[134:135], v[132:133], 0, v[134:135]
	s_mov_b32 s5, 0x80000
	s_mov_b64 s[6:7], 0x80000
	v_cvt_pk_bf16_f32 v62, v62, v63
	v_cvt_pk_bf16_f32 v63, v64, v65
	v_cvt_pk_bf16_f32 v64, v58, v59
	v_add_co_u32_e32 v58, vcc, s5, v134
	v_cvt_pk_bf16_f32 v70, v70, v71
	v_cvt_pk_bf16_f32 v71, v72, v73
	v_cvt_pk_bf16_f32 v72, v66, v67
	v_lshl_add_u64 v[66:67], v[134:135], 0, s[6:7]
	v_addc_co_u32_e32 v59, vcc, 0, v135, vcc
	v_cvt_pk_bf16_f32 v46, v46, v47
	v_cvt_pk_bf16_f32 v47, v48, v49
	v_cvt_pk_bf16_f32 v48, v42, v43
	v_cvt_pk_bf16_f32 v49, v44, v45
	s_mov_b32 s5, 0x90000
	v_cvt_pk_bf16_f32 v110, v110, v111
	v_cvt_pk_bf16_f32 v111, v112, v113
	v_cvt_pk_bf16_f32 v112, v106, v107
	v_or_b32_e32 v106, 16, v130
	global_store_dwordx4 v[66:67], v[46:49], off offset:256
	s_mov_b64 s[6:7], 0x90000
	v_ashrrev_i32_e32 v107, 31, v106
	v_add_co_u32_e32 v48, vcc, s5, v134
	v_cvt_pk_bf16_f32 v94, v94, v95
	v_cvt_pk_bf16_f32 v95, v96, v97
	v_cvt_pk_bf16_f32 v96, v90, v91
	v_or_b32_e32 v90, 32, v130
	v_lshl_add_u64 v[46:47], v[134:135], 0, s[6:7]
	v_addc_co_u32_e32 v49, vcc, 0, v135, vcc
	v_cvt_pk_bf16_f32 v30, v30, v31
	v_cvt_pk_bf16_f32 v31, v32, v33
	v_cvt_pk_bf16_f32 v32, v26, v27
	v_cvt_pk_bf16_f32 v33, v28, v29
	s_mov_b32 s5, 0xa0000
	v_cvt_pk_bf16_f32 v113, v108, v109
	v_lshlrev_b64 v[106:107], 12, v[106:107]
	v_ashrrev_i32_e32 v91, 31, v90
	v_cvt_pk_bf16_f32 v78, v78, v79
	v_cvt_pk_bf16_f32 v79, v80, v81
	v_cvt_pk_bf16_f32 v80, v74, v75
	v_or_b32_e32 v74, 48, v130
	global_store_dwordx4 v[46:47], v[30:33], off offset:256
	s_mov_b64 s[6:7], 0xa0000
	global_store_dwordx4 v[134:135], v[110:113], off offset:256
	v_add_co_u32_e32 v32, vcc, s5, v134
	s_nop 0
	v_lshl_add_u64 v[110:111], v[132:133], 0, v[106:107]
	v_cvt_pk_bf16_f32 v97, v92, v93
	v_lshlrev_b64 v[90:91], 12, v[90:91]
	v_ashrrev_i32_e32 v75, 31, v74
	v_lshl_add_u64 v[30:31], v[134:135], 0, s[6:7]
	v_addc_co_u32_e32 v33, vcc, 0, v135, vcc
	v_cvt_pk_bf16_f32 v14, v14, v15
	v_cvt_pk_bf16_f32 v15, v16, v17
	v_cvt_pk_bf16_f32 v16, v10, v11
	v_cvt_pk_bf16_f32 v17, v12, v13
	s_mov_b32 s5, 0xb0000
	global_store_dwordx4 v[110:111], v[94:97], off offset:256
	v_cvt_pk_bf16_f32 v81, v76, v77
	v_lshlrev_b64 v[74:75], 12, v[74:75]
	v_lshl_add_u64 v[94:95], v[132:133], 0, v[90:91]
	global_store_dwordx4 v[30:31], v[14:17], off offset:256
	s_mov_b64 s[6:7], 0xb0000
	v_cvt_pk_bf16_f32 v126, v126, v127
	v_add_co_u32_e32 v16, vcc, s5, v134
	v_cvt_pk_bf16_f32 v127, v128, v129
	v_cvt_pk_bf16_f32 v128, v122, v123
	v_cvt_pk_bf16_f32 v129, v124, v125
	v_cvt_pk_bf16_f32 v106, v118, v119
	v_cvt_pk_bf16_f32 v107, v120, v121
	v_cvt_pk_bf16_f32 v108, v114, v115
	v_cvt_pk_bf16_f32 v109, v116, v117
	v_cvt_pk_bf16_f32 v90, v102, v103
	v_cvt_pk_bf16_f32 v91, v104, v105
	v_cvt_pk_bf16_f32 v92, v98, v99
	v_cvt_pk_bf16_f32 v93, v100, v101
	global_store_dwordx4 v[94:95], v[78:81], off offset:256
	v_cvt_pk_bf16_f32 v76, v82, v83
	v_cvt_pk_bf16_f32 v77, v84, v85
	v_lshl_add_u64 v[78:79], v[132:133], 0, v[74:75]
	v_cvt_pk_bf16_f32 v74, v86, v87
	v_cvt_pk_bf16_f32 v75, v88, v89
	v_cvt_pk_bf16_f32 v73, v68, v69
	v_cvt_pk_bf16_f32 v65, v60, v61
	v_cvt_pk_bf16_f32 v42, v54, v55
	v_cvt_pk_bf16_f32 v43, v56, v57
	v_cvt_pk_bf16_f32 v44, v50, v51
	v_cvt_pk_bf16_f32 v45, v52, v53
	v_cvt_pk_bf16_f32 v26, v38, v39
	v_cvt_pk_bf16_f32 v27, v40, v41
	v_cvt_pk_bf16_f32 v28, v34, v35
	v_cvt_pk_bf16_f32 v29, v36, v37
	v_lshl_add_u64 v[14:15], v[134:135], 0, s[6:7]
	v_cvt_pk_bf16_f32 v10, v22, v23
	v_cvt_pk_bf16_f32 v11, v24, v25
	v_cvt_pk_bf16_f32 v12, v18, v19
	v_cvt_pk_bf16_f32 v13, v20, v21
	v_addc_co_u32_e32 v17, vcc, 0, v135, vcc
	v_cvt_pk_bf16_f32 v6, v6, v7
	v_cvt_pk_bf16_f32 v7, v8, v9
	v_cvt_pk_bf16_f32 v8, v2, v3
	v_cvt_pk_bf16_f32 v9, v4, v5
	global_store_dwordx4 v[134:135], v[126:129], off
	global_store_dwordx4 v[110:111], v[106:109], off
	global_store_dwordx4 v[94:95], v[90:93], off
	global_store_dwordx4 v[78:79], v[74:77], off
	global_store_dwordx4 v[78:79], v[70:73], off offset:256
	global_store_dwordx4 v[58:59], v[62:65], off
	global_store_dwordx4 v[48:49], v[42:45], off
	global_store_dwordx4 v[32:33], v[26:29], off
	global_store_dwordx4 v[16:17], v[10:13], off
	global_store_dwordx4 v[14:15], v[6:9], off offset:256
	s_waitcnt vmcnt(0)
	s_cmpk_lt_u32 s4, 0x100
	s_cbranch_scc0 .LBB0_166
	s_barrier

.LBB0_246:
	s_add_i32 s76, s88, 2
	s_add_u32 s33, s0, 0xfff80080
	s_addc_u32 s48, s1, -1
	s_add_i32 m0, s35, 0xc000
	s_add_i32 s77, s35, 0xe000
	global_load_lds_dwordx4 v146, s[0:1]
	s_mov_b32 m0, s77
	s_cmp_eq_u32 vcc_hi, s88
	global_load_lds_dwordx4 v148, s[0:1]
	s_cselect_b32 s88, vcc_lo, s56
	s_cselect_b32 s91, s69, s48
	s_cselect_b32 s90, s75, s33
	s_cselect_b32 s89, s73, s57
	s_add_i32 s33, 0, 0x10000
	s_add_i32 s96, 0, 0x14000
	ds_read_b128 v[150:153], v246
	ds_read_b128 v[154:157], v246 offset:1024
	ds_read_b128 v[158:161], v246 offset:2048
	ds_read_b128 v[162:165], v246 offset:3072
	ds_read_b128 v[166:169], v247
	ds_read_b128 v[170:173], v247 offset:1024
	ds_read_b128 v[174:177], v247 offset:2048
	ds_read_b128 v[178:181], v247 offset:3072
	ds_read_b128 v[182:185], v141
	ds_read_b128 v[186:189], v141 offset:1024
	ds_read_b128 v[190:193], v141 offset:2048
	ds_read_b128 v[194:197], v141 offset:3072
	ds_read_b128 v[198:201], v141 offset:4096
	ds_read_b128 v[202:205], v141 offset:5120
	ds_read_b128 v[210:213], v141 offset:6144
	ds_read_b128 v[214:217], v141 offset:7168
	s_waitcnt vmcnt(8)
	s_waitcnt lgkmcnt(0)
	s_barrier
	s_setprio 1
	s_waitcnt lgkmcnt(0)
	v_mfma_f32_16x16x32_bf16 v[128:131], v[150:153], v[182:185], v[128:131]
	v_mfma_f32_16x16x32_bf16 v[124:127], v[158:161], v[182:185], v[124:127]
	v_mfma_f32_16x16x32_bf16 v[116:119], v[150:153], v[190:193], v[116:119]
	v_mfma_f32_16x16x32_bf16 v[108:111], v[158:161], v[190:193], v[108:111]
	v_mfma_f32_16x16x32_bf16 v[100:103], v[150:153], v[198:201], v[100:103]
	v_mfma_f32_16x16x32_bf16 v[92:95], v[158:161], v[198:201], v[92:95]
	v_mfma_f32_16x16x32_bf16 v[84:87], v[150:153], v[210:213], v[84:87]
	v_mfma_f32_16x16x32_bf16 v[76:79], v[158:161], v[210:213], v[76:79]
	v_mfma_f32_16x16x32_bf16 v[128:131], v[154:157], v[186:189], v[128:131]
	v_mfma_f32_16x16x32_bf16 v[124:127], v[162:165], v[186:189], v[124:127]
	v_mfma_f32_16x16x32_bf16 v[116:119], v[154:157], v[194:197], v[116:119]
	v_mfma_f32_16x16x32_bf16 v[108:111], v[162:165], v[194:197], v[108:111]
	v_mfma_f32_16x16x32_bf16 v[100:103], v[154:157], v[202:205], v[100:103]
	v_mfma_f32_16x16x32_bf16 v[92:95], v[162:165], v[202:205], v[92:95]
	v_mfma_f32_16x16x32_bf16 v[84:87], v[154:157], v[214:217], v[84:87]
	v_mfma_f32_16x16x32_bf16 v[76:79], v[162:165], v[214:217], v[76:79]
	v_mfma_f32_16x16x32_bf16 v[120:123], v[166:169], v[182:185], v[120:123]
	v_mfma_f32_16x16x32_bf16 v[112:115], v[174:177], v[182:185], v[112:115]
	v_mfma_f32_16x16x32_bf16 v[104:107], v[166:169], v[190:193], v[104:107]
	v_mfma_f32_16x16x32_bf16 v[96:99], v[174:177], v[190:193], v[96:99]
	v_mfma_f32_16x16x32_bf16 v[88:91], v[166:169], v[198:201], v[88:91]
	v_mfma_f32_16x16x32_bf16 v[80:83], v[174:177], v[198:201], v[80:83]
	v_mfma_f32_16x16x32_bf16 v[72:75], v[166:169], v[210:213], v[72:75]
	v_mfma_f32_16x16x32_bf16 v[68:71], v[174:177], v[210:213], v[68:71]
	v_mfma_f32_16x16x32_bf16 v[120:123], v[170:173], v[186:189], v[120:123]
	v_mfma_f32_16x16x32_bf16 v[112:115], v[178:181], v[186:189], v[112:115]
	v_mfma_f32_16x16x32_bf16 v[104:107], v[170:173], v[194:197], v[104:107]
	v_mfma_f32_16x16x32_bf16 v[96:99], v[178:181], v[194:197], v[96:99]
	v_mfma_f32_16x16x32_bf16 v[88:91], v[170:173], v[202:205], v[88:91]
	v_mfma_f32_16x16x32_bf16 v[80:83], v[178:181], v[202:205], v[80:83]
	v_mfma_f32_16x16x32_bf16 v[72:75], v[170:173], v[214:217], v[72:75]
	v_mfma_f32_16x16x32_bf16 v[68:71], v[178:181], v[214:217], v[68:71]
	s_setprio 0
	s_barrier
	s_add_i32 s48, s33, s29
	s_mov_b32 m0, s48
	s_nop 0
	global_load_lds_dwordx4 v134, s[88:89]
	s_add_i32 m0, s48, 0x2000
	s_add_u32 s78, s88, 0x80000
	s_addc_u32 s79, s89, 0
	s_add_i32 s48, s96, s29
	global_load_lds_dwordx4 v138, s[88:89]
	s_mov_b32 m0, s48
	s_nop 0
	global_load_lds_dwordx4 v134, s[78:79]
	s_add_i32 m0, s48, 0x2000
	s_nop 0
	global_load_lds_dwordx4 v138, s[78:79]
	s_mov_b32 m0, s35
	s_nop 0
	global_load_lds_dwordx4 v132, s[90:91]
	s_mov_b32 m0, s60
	s_nop 0
	global_load_lds_dwordx4 v136, s[90:91]
	ds_read_b128 v[182:185], v141 offset:16384
	ds_read_b128 v[186:189], v141 offset:17408
	ds_read_b128 v[190:193], v141 offset:18432
	ds_read_b128 v[194:197], v141 offset:19456
	ds_read_b128 v[198:201], v141 offset:20480
	ds_read_b128 v[202:205], v141 offset:21504
	ds_read_b128 v[210:213], v141 offset:22528
	ds_read_b128 v[214:217], v141 offset:23552
	s_waitcnt vmcnt(8)
	s_waitcnt lgkmcnt(0)
	s_barrier
	s_setprio 1
	s_waitcnt lgkmcnt(0)
	v_mfma_f32_16x16x32_bf16 v[64:67], v[150:153], v[182:185], v[64:67]
	v_mfma_f32_16x16x32_bf16 v[60:63], v[158:161], v[182:185], v[60:63]
	v_mfma_f32_16x16x32_bf16 v[52:55], v[150:153], v[190:193], v[52:55]
	v_mfma_f32_16x16x32_bf16 v[44:47], v[158:161], v[190:193], v[44:47]
	v_mfma_f32_16x16x32_bf16 v[36:39], v[150:153], v[198:201], v[36:39]
	v_mfma_f32_16x16x32_bf16 v[28:31], v[158:161], v[198:201], v[28:31]
	v_mfma_f32_16x16x32_bf16 v[20:23], v[150:153], v[210:213], v[20:23]
	v_mfma_f32_16x16x32_bf16 v[12:15], v[158:161], v[210:213], v[12:15]
	v_mfma_f32_16x16x32_bf16 v[64:67], v[154:157], v[186:189], v[64:67]
	v_mfma_f32_16x16x32_bf16 v[60:63], v[162:165], v[186:189], v[60:63]
	v_mfma_f32_16x16x32_bf16 v[52:55], v[154:157], v[194:197], v[52:55]
	v_mfma_f32_16x16x32_bf16 v[44:47], v[162:165], v[194:197], v[44:47]
	v_mfma_f32_16x16x32_bf16 v[36:39], v[154:157], v[202:205], v[36:39]
	v_mfma_f32_16x16x32_bf16 v[28:31], v[162:165], v[202:205], v[28:31]
	v_mfma_f32_16x16x32_bf16 v[20:23], v[154:157], v[214:217], v[20:23]
	v_mfma_f32_16x16x32_bf16 v[12:15], v[162:165], v[214:217], v[12:15]
	v_mfma_f32_16x16x32_bf16 v[56:59], v[166:169], v[182:185], v[56:59]
	v_mfma_f32_16x16x32_bf16 v[48:51], v[174:177], v[182:185], v[48:51]
	v_mfma_f32_16x16x32_bf16 v[40:43], v[166:169], v[190:193], v[40:43]
	v_mfma_f32_16x16x32_bf16 v[32:35], v[174:177], v[190:193], v[32:35]
	v_mfma_f32_16x16x32_bf16 v[24:27], v[166:169], v[198:201], v[24:27]
	v_mfma_f32_16x16x32_bf16 v[16:19], v[174:177], v[198:201], v[16:19]
	v_mfma_f32_16x16x32_bf16 v[8:11], v[166:169], v[210:213], v[8:11]
	v_mfma_f32_16x16x32_bf16 v[4:7], v[174:177], v[210:213], v[4:7]
	v_mfma_f32_16x16x32_bf16 v[56:59], v[170:173], v[186:189], v[56:59]
	v_mfma_f32_16x16x32_bf16 v[48:51], v[178:181], v[186:189], v[48:51]
	v_mfma_f32_16x16x32_bf16 v[40:43], v[170:173], v[194:197], v[40:43]
	v_mfma_f32_16x16x32_bf16 v[32:35], v[178:181], v[194:197], v[32:35]
	v_mfma_f32_16x16x32_bf16 v[24:27], v[170:173], v[202:205], v[24:27]
	v_mfma_f32_16x16x32_bf16 v[16:19], v[178:181], v[202:205], v[16:19]
	v_mfma_f32_16x16x32_bf16 v[8:11], v[170:173], v[214:217], v[8:11]
	v_mfma_f32_16x16x32_bf16 v[4:7], v[178:181], v[214:217], v[4:7]
	s_setprio 0
	s_barrier
	s_add_u32 s78, s90, 0x80000
	s_addc_u32 s79, s91, 0
	s_mov_b32 m0, s61
	s_nop 0
	global_load_lds_dwordx4 v132, s[78:79]
	s_mov_b32 m0, s62
	s_nop 0
	global_load_lds_dwordx4 v136, s[78:79]
	s_add_i32 s97, 0, 0x18000
	s_add_i32 s48, 0, 0x1c000
	ds_read_b128 v[150:153], v248
	ds_read_b128 v[154:157], v248 offset:1024
	ds_read_b128 v[158:161], v248 offset:2048
	ds_read_b128 v[162:165], v248 offset:3072
	ds_read_b128 v[166:169], v249
	ds_read_b128 v[170:173], v249 offset:1024
	ds_read_b128 v[174:177], v249 offset:2048
	ds_read_b128 v[178:181], v249 offset:3072
	ds_read_b128 v[182:185], v141 offset:32768
	ds_read_b128 v[186:189], v141 offset:33792
	ds_read_b128 v[190:193], v141 offset:34816
	ds_read_b128 v[194:197], v141 offset:35840
	ds_read_b128 v[198:201], v141 offset:36864
	ds_read_b128 v[202:205], v141 offset:37888
	ds_read_b128 v[210:213], v141 offset:38912
	ds_read_b128 v[214:217], v141 offset:39936
	s_waitcnt vmcnt(8)
	s_waitcnt lgkmcnt(0)
	s_barrier
	s_setprio 1
	s_waitcnt lgkmcnt(0)
	v_mfma_f32_16x16x32_bf16 v[128:131], v[150:153], v[182:185], v[128:131]
	v_mfma_f32_16x16x32_bf16 v[124:127], v[158:161], v[182:185], v[124:127]
	v_mfma_f32_16x16x32_bf16 v[116:119], v[150:153], v[190:193], v[116:119]
	v_mfma_f32_16x16x32_bf16 v[108:111], v[158:161], v[190:193], v[108:111]
	v_mfma_f32_16x16x32_bf16 v[100:103], v[150:153], v[198:201], v[100:103]
	v_mfma_f32_16x16x32_bf16 v[92:95], v[158:161], v[198:201], v[92:95]
	v_mfma_f32_16x16x32_bf16 v[84:87], v[150:153], v[210:213], v[84:87]
	v_mfma_f32_16x16x32_bf16 v[76:79], v[158:161], v[210:213], v[76:79]
	v_mfma_f32_16x16x32_bf16 v[128:131], v[154:157], v[186:189], v[128:131]
	v_mfma_f32_16x16x32_bf16 v[124:127], v[162:165], v[186:189], v[124:127]
	v_mfma_f32_16x16x32_bf16 v[116:119], v[154:157], v[194:197], v[116:119]
	v_mfma_f32_16x16x32_bf16 v[108:111], v[162:165], v[194:197], v[108:111]
	v_mfma_f32_16x16x32_bf16 v[100:103], v[154:157], v[202:205], v[100:103]
	v_mfma_f32_16x16x32_bf16 v[92:95], v[162:165], v[202:205], v[92:95]
	v_mfma_f32_16x16x32_bf16 v[84:87], v[154:157], v[214:217], v[84:87]
	v_mfma_f32_16x16x32_bf16 v[76:79], v[162:165], v[214:217], v[76:79]
	v_mfma_f32_16x16x32_bf16 v[120:123], v[166:169], v[182:185], v[120:123]
	v_mfma_f32_16x16x32_bf16 v[112:115], v[174:177], v[182:185], v[112:115]
	v_mfma_f32_16x16x32_bf16 v[104:107], v[166:169], v[190:193], v[104:107]
	v_mfma_f32_16x16x32_bf16 v[96:99], v[174:177], v[190:193], v[96:99]
	v_mfma_f32_16x16x32_bf16 v[88:91], v[166:169], v[198:201], v[88:91]
	v_mfma_f32_16x16x32_bf16 v[80:83], v[174:177], v[198:201], v[80:83]
	v_mfma_f32_16x16x32_bf16 v[72:75], v[166:169], v[210:213], v[72:75]
	v_mfma_f32_16x16x32_bf16 v[68:71], v[174:177], v[210:213], v[68:71]
	v_mfma_f32_16x16x32_bf16 v[120:123], v[170:173], v[186:189], v[120:123]
	v_mfma_f32_16x16x32_bf16 v[112:115], v[178:181], v[186:189], v[112:115]
	v_mfma_f32_16x16x32_bf16 v[104:107], v[170:173], v[194:197], v[104:107]
	v_mfma_f32_16x16x32_bf16 v[96:99], v[178:181], v[194:197], v[96:99]
	v_mfma_f32_16x16x32_bf16 v[88:91], v[170:173], v[202:205], v[88:91]
	v_mfma_f32_16x16x32_bf16 v[80:83], v[178:181], v[202:205], v[80:83]
	v_mfma_f32_16x16x32_bf16 v[72:75], v[170:173], v[214:217], v[72:75]
	v_mfma_f32_16x16x32_bf16 v[68:71], v[178:181], v[214:217], v[68:71]
	s_setprio 0
	s_barrier
	s_add_i32 s77, s97, s29
	s_mov_b32 m0, s77
	s_nop 0
	s_add_u32 s98, s88, 0x80
	s_addc_u32 s99, s89, 0
	s_nop 0
	global_load_lds_dwordx4 v134, s[98:99]
	s_add_i32 m0, s77, 0x2000
	s_add_u32 s78, s88, 0x80080
	s_addc_u32 s79, s89, 0
	s_add_i32 s77, s48, s29
	global_load_lds_dwordx4 v138, s[98:99]
	s_mov_b32 m0, s77
	s_nop 0
	global_load_lds_dwordx4 v134, s[78:79]
	s_add_i32 m0, s77, 0x2000
	s_nop 0
	global_load_lds_dwordx4 v138, s[78:79]
	s_mov_b32 m0, s63
	s_nop 0
	s_add_u32 s98, s90, 0x80
	s_addc_u32 s99, s91, 0
	s_nop 0
	global_load_lds_dwordx4 v132, s[98:99]
	s_mov_b32 m0, s64
	s_nop 0
	global_load_lds_dwordx4 v136, s[98:99]
	ds_read_b128 v[182:185], v141 offset:49152
	ds_read_b128 v[186:189], v141 offset:50176
	ds_read_b128 v[190:193], v141 offset:51200
	ds_read_b128 v[194:197], v141 offset:52224
	ds_read_b128 v[198:201], v141 offset:53248
	ds_read_b128 v[202:205], v141 offset:54272
	ds_read_b128 v[210:213], v141 offset:55296
	ds_read_b128 v[214:217], v141 offset:56320
	s_waitcnt vmcnt(8)
	s_waitcnt lgkmcnt(0)
	s_barrier
	s_setprio 1
	s_waitcnt lgkmcnt(0)
	v_mfma_f32_16x16x32_bf16 v[64:67], v[150:153], v[182:185], v[64:67]
	v_mfma_f32_16x16x32_bf16 v[60:63], v[158:161], v[182:185], v[60:63]
	v_mfma_f32_16x16x32_bf16 v[52:55], v[150:153], v[190:193], v[52:55]
	v_mfma_f32_16x16x32_bf16 v[44:47], v[158:161], v[190:193], v[44:47]
	v_mfma_f32_16x16x32_bf16 v[36:39], v[150:153], v[198:201], v[36:39]
	v_mfma_f32_16x16x32_bf16 v[28:31], v[158:161], v[198:201], v[28:31]
	v_mfma_f32_16x16x32_bf16 v[20:23], v[150:153], v[210:213], v[20:23]
	v_mfma_f32_16x16x32_bf16 v[12:15], v[158:161], v[210:213], v[12:15]
	v_mfma_f32_16x16x32_bf16 v[64:67], v[154:157], v[186:189], v[64:67]
	v_mfma_f32_16x16x32_bf16 v[60:63], v[162:165], v[186:189], v[60:63]
	v_mfma_f32_16x16x32_bf16 v[52:55], v[154:157], v[194:197], v[52:55]
	v_mfma_f32_16x16x32_bf16 v[44:47], v[162:165], v[194:197], v[44:47]
	v_mfma_f32_16x16x32_bf16 v[36:39], v[154:157], v[202:205], v[36:39]
	v_mfma_f32_16x16x32_bf16 v[28:31], v[162:165], v[202:205], v[28:31]
	v_mfma_f32_16x16x32_bf16 v[20:23], v[154:157], v[214:217], v[20:23]
	v_mfma_f32_16x16x32_bf16 v[12:15], v[162:165], v[214:217], v[12:15]
	v_mfma_f32_16x16x32_bf16 v[56:59], v[166:169], v[182:185], v[56:59]
	v_mfma_f32_16x16x32_bf16 v[48:51], v[174:177], v[182:185], v[48:51]
	v_mfma_f32_16x16x32_bf16 v[40:43], v[166:169], v[190:193], v[40:43]
	v_mfma_f32_16x16x32_bf16 v[32:35], v[174:177], v[190:193], v[32:35]
	v_mfma_f32_16x16x32_bf16 v[24:27], v[166:169], v[198:201], v[24:27]
	v_mfma_f32_16x16x32_bf16 v[16:19], v[174:177], v[198:201], v[16:19]
	v_mfma_f32_16x16x32_bf16 v[8:11], v[166:169], v[210:213], v[8:11]
	v_mfma_f32_16x16x32_bf16 v[4:7], v[174:177], v[210:213], v[4:7]
	v_mfma_f32_16x16x32_bf16 v[56:59], v[170:173], v[186:189], v[56:59]
	v_mfma_f32_16x16x32_bf16 v[48:51], v[178:181], v[186:189], v[48:51]
	v_mfma_f32_16x16x32_bf16 v[40:43], v[170:173], v[194:197], v[40:43]
	v_mfma_f32_16x16x32_bf16 v[32:35], v[178:181], v[194:197], v[32:35]
	v_mfma_f32_16x16x32_bf16 v[24:27], v[170:173], v[202:205], v[24:27]
	v_mfma_f32_16x16x32_bf16 v[16:19], v[178:181], v[202:205], v[16:19]
	v_mfma_f32_16x16x32_bf16 v[8:11], v[170:173], v[214:217], v[8:11]
	v_mfma_f32_16x16x32_bf16 v[4:7], v[178:181], v[214:217], v[4:7]
	s_setprio 0
	s_barrier
	s_add_u32 s0, s0, 0x100
	s_addc_u32 s1, s1, 0
	s_add_u32 s56, s56, 0x100
	s_addc_u32 s57, s57, 0
	s_cmp_ge_i32 s76, s55
	s_mov_b32 s88, s76
	s_cbranch_scc0 .LBB0_246
	s_and_b64 vcc, exec, s[58:59]
	s_cbranch_vccz .LBB0_249
	s_barrier

.LBB0_521:
	s_add_i32 s55, s54, 2
	s_add_u32 s56, s74, 0xfff80080
	s_addc_u32 s57, s75, -1
	s_add_i32 m0, s17, 0xc000
	s_add_i32 s76, s17, 0xe000
	global_load_lds_dwordx4 v138, s[74:75]
	s_mov_b32 m0, s76
	s_cmp_eq_u32 s9, s54
	global_load_lds_dwordx4 v140, s[74:75]
	s_cselect_b32 s87, s69, s57
	s_cselect_b32 s86, s68, s56
	s_cselect_b32 s85, s73, s35
	s_cselect_b32 s84, s72, s23
	ds_read_b128 v[146:149], v246
	ds_read_b128 v[150:153], v246 offset:1024
	ds_read_b128 v[154:157], v246 offset:2048
	ds_read_b128 v[158:161], v246 offset:3072
	ds_read_b128 v[162:165], v247
	ds_read_b128 v[166:169], v247 offset:1024
	ds_read_b128 v[170:173], v247 offset:2048
	ds_read_b128 v[174:177], v247 offset:3072
	ds_read_b128 v[178:181], v144
	ds_read_b128 v[182:185], v144 offset:1024
	ds_read_b128 v[186:189], v144 offset:2048
	ds_read_b128 v[190:193], v144 offset:3072
	ds_read_b128 v[194:197], v144 offset:4096
	ds_read_b128 v[198:201], v144 offset:5120
	ds_read_b128 v[202:205], v144 offset:6144
	ds_read_b128 v[210:213], v144 offset:7168
	s_waitcnt vmcnt(8)
	s_waitcnt lgkmcnt(0)
	s_barrier
	s_setprio 1
	s_waitcnt lgkmcnt(0)
	v_mfma_f32_16x16x32_bf16 v[128:131], v[146:149], v[178:181], v[128:131]
	v_mfma_f32_16x16x32_bf16 v[124:127], v[154:157], v[178:181], v[124:127]
	v_mfma_f32_16x16x32_bf16 v[120:123], v[146:149], v[186:189], v[120:123]
	v_mfma_f32_16x16x32_bf16 v[116:119], v[154:157], v[186:189], v[116:119]
	v_mfma_f32_16x16x32_bf16 v[104:107], v[146:149], v[194:197], v[104:107]
	v_mfma_f32_16x16x32_bf16 v[100:103], v[154:157], v[194:197], v[100:103]
	v_mfma_f32_16x16x32_bf16 v[88:91], v[146:149], v[202:205], v[88:91]
	v_mfma_f32_16x16x32_bf16 v[84:87], v[154:157], v[202:205], v[84:87]
	v_mfma_f32_16x16x32_bf16 v[128:131], v[150:153], v[182:185], v[128:131]
	v_mfma_f32_16x16x32_bf16 v[124:127], v[158:161], v[182:185], v[124:127]
	v_mfma_f32_16x16x32_bf16 v[120:123], v[150:153], v[190:193], v[120:123]
	v_mfma_f32_16x16x32_bf16 v[116:119], v[158:161], v[190:193], v[116:119]
	v_mfma_f32_16x16x32_bf16 v[104:107], v[150:153], v[198:201], v[104:107]
	v_mfma_f32_16x16x32_bf16 v[100:103], v[158:161], v[198:201], v[100:103]
	v_mfma_f32_16x16x32_bf16 v[88:91], v[150:153], v[210:213], v[88:91]
	v_mfma_f32_16x16x32_bf16 v[84:87], v[158:161], v[210:213], v[84:87]
	v_mfma_f32_16x16x32_bf16 v[112:115], v[162:165], v[178:181], v[112:115]
	v_mfma_f32_16x16x32_bf16 v[108:111], v[170:173], v[178:181], v[108:111]
	v_mfma_f32_16x16x32_bf16 v[96:99], v[162:165], v[186:189], v[96:99]
	v_mfma_f32_16x16x32_bf16 v[92:95], v[170:173], v[186:189], v[92:95]
	v_mfma_f32_16x16x32_bf16 v[80:83], v[162:165], v[194:197], v[80:83]
	v_mfma_f32_16x16x32_bf16 v[76:79], v[170:173], v[194:197], v[76:79]
	v_mfma_f32_16x16x32_bf16 v[72:75], v[162:165], v[202:205], v[72:75]
	v_mfma_f32_16x16x32_bf16 v[68:71], v[170:173], v[202:205], v[68:71]
	v_mfma_f32_16x16x32_bf16 v[112:115], v[166:169], v[182:185], v[112:115]
	v_mfma_f32_16x16x32_bf16 v[108:111], v[174:177], v[182:185], v[108:111]
	v_mfma_f32_16x16x32_bf16 v[96:99], v[166:169], v[190:193], v[96:99]
	v_mfma_f32_16x16x32_bf16 v[92:95], v[174:177], v[190:193], v[92:95]
	v_mfma_f32_16x16x32_bf16 v[80:83], v[166:169], v[198:201], v[80:83]
	v_mfma_f32_16x16x32_bf16 v[76:79], v[174:177], v[198:201], v[76:79]
	v_mfma_f32_16x16x32_bf16 v[72:75], v[166:169], v[210:213], v[72:75]
	v_mfma_f32_16x16x32_bf16 v[68:71], v[174:177], v[210:213], v[68:71]
	s_setprio 0
	s_barrier
	s_add_i32 s54, s33, s16
	s_mov_b32 m0, s54
	s_nop 0
	global_load_lds_dwordx4 v2, s[84:85]
	s_add_i32 m0, s54, 0x2000
	s_add_u32 s56, s84, 0x80000
	s_addc_u32 s57, s85, 0
	s_add_i32 s54, s96, s16
	global_load_lds_dwordx4 v136, s[84:85]
	s_mov_b32 m0, s54
	s_nop 0
	global_load_lds_dwordx4 v2, s[56:57]
	s_add_i32 m0, s54, 0x2000
	s_nop 0
	global_load_lds_dwordx4 v136, s[56:57]
	s_mov_b32 m0, s17
	s_nop 0
	global_load_lds_dwordx4 v132, s[86:87]
	s_mov_b32 m0, s29
	s_nop 0
	global_load_lds_dwordx4 v134, s[86:87]
	ds_read_b128 v[178:181], v144 offset:16384
	ds_read_b128 v[182:185], v144 offset:17408
	ds_read_b128 v[186:189], v144 offset:18432
	ds_read_b128 v[190:193], v144 offset:19456
	ds_read_b128 v[194:197], v144 offset:20480
	ds_read_b128 v[198:201], v144 offset:21504
	ds_read_b128 v[202:205], v144 offset:22528
	ds_read_b128 v[210:213], v144 offset:23552
	s_waitcnt vmcnt(8)
	s_waitcnt lgkmcnt(0)
	s_barrier
	s_setprio 1
	s_waitcnt lgkmcnt(0)
	v_mfma_f32_16x16x32_bf16 v[64:67], v[146:149], v[178:181], v[64:67]
	v_mfma_f32_16x16x32_bf16 v[60:63], v[154:157], v[178:181], v[60:63]
	v_mfma_f32_16x16x32_bf16 v[56:59], v[146:149], v[186:189], v[56:59]
	v_mfma_f32_16x16x32_bf16 v[52:55], v[154:157], v[186:189], v[52:55]
	v_mfma_f32_16x16x32_bf16 v[40:43], v[146:149], v[194:197], v[40:43]
	v_mfma_f32_16x16x32_bf16 v[36:39], v[154:157], v[194:197], v[36:39]
	v_mfma_f32_16x16x32_bf16 v[24:27], v[146:149], v[202:205], v[24:27]
	v_mfma_f32_16x16x32_bf16 v[20:23], v[154:157], v[202:205], v[20:23]
	v_mfma_f32_16x16x32_bf16 v[64:67], v[150:153], v[182:185], v[64:67]
	v_mfma_f32_16x16x32_bf16 v[60:63], v[158:161], v[182:185], v[60:63]
	v_mfma_f32_16x16x32_bf16 v[56:59], v[150:153], v[190:193], v[56:59]
	v_mfma_f32_16x16x32_bf16 v[52:55], v[158:161], v[190:193], v[52:55]
	v_mfma_f32_16x16x32_bf16 v[40:43], v[150:153], v[198:201], v[40:43]
	v_mfma_f32_16x16x32_bf16 v[36:39], v[158:161], v[198:201], v[36:39]
	v_mfma_f32_16x16x32_bf16 v[24:27], v[150:153], v[210:213], v[24:27]
	v_mfma_f32_16x16x32_bf16 v[20:23], v[158:161], v[210:213], v[20:23]
	v_mfma_f32_16x16x32_bf16 v[48:51], v[162:165], v[178:181], v[48:51]
	v_mfma_f32_16x16x32_bf16 v[44:47], v[170:173], v[178:181], v[44:47]
	v_mfma_f32_16x16x32_bf16 v[32:35], v[162:165], v[186:189], v[32:35]
	v_mfma_f32_16x16x32_bf16 v[28:31], v[170:173], v[186:189], v[28:31]
	v_mfma_f32_16x16x32_bf16 v[16:19], v[162:165], v[194:197], v[16:19]
	v_mfma_f32_16x16x32_bf16 v[12:15], v[170:173], v[194:197], v[12:15]
	v_mfma_f32_16x16x32_bf16 v[8:11], v[162:165], v[202:205], v[8:11]
	v_mfma_f32_16x16x32_bf16 v[4:7], v[170:173], v[202:205], v[4:7]
	v_mfma_f32_16x16x32_bf16 v[48:51], v[166:169], v[182:185], v[48:51]
	v_mfma_f32_16x16x32_bf16 v[44:47], v[174:177], v[182:185], v[44:47]
	v_mfma_f32_16x16x32_bf16 v[32:35], v[166:169], v[190:193], v[32:35]
	v_mfma_f32_16x16x32_bf16 v[28:31], v[174:177], v[190:193], v[28:31]
	v_mfma_f32_16x16x32_bf16 v[16:19], v[166:169], v[198:201], v[16:19]
	v_mfma_f32_16x16x32_bf16 v[12:15], v[174:177], v[198:201], v[12:15]
	v_mfma_f32_16x16x32_bf16 v[8:11], v[166:169], v[210:213], v[8:11]
	v_mfma_f32_16x16x32_bf16 v[4:7], v[174:177], v[210:213], v[4:7]
	s_setprio 0
	s_barrier
	s_add_u32 s56, s86, 0x80000
	s_addc_u32 s57, s87, 0
	s_mov_b32 m0, s60
	s_nop 0
	global_load_lds_dwordx4 v132, s[56:57]
	s_mov_b32 m0, s61
	s_nop 0
	global_load_lds_dwordx4 v134, s[56:57]
	ds_read_b128 v[146:149], v248
	ds_read_b128 v[150:153], v248 offset:1024
	ds_read_b128 v[154:157], v248 offset:2048
	ds_read_b128 v[158:161], v248 offset:3072
	ds_read_b128 v[162:165], v249
	ds_read_b128 v[166:169], v249 offset:1024
	ds_read_b128 v[170:173], v249 offset:2048
	ds_read_b128 v[174:177], v249 offset:3072
	ds_read_b128 v[178:181], v144 offset:32768
	ds_read_b128 v[182:185], v144 offset:33792
	ds_read_b128 v[186:189], v144 offset:34816
	ds_read_b128 v[190:193], v144 offset:35840
	ds_read_b128 v[194:197], v144 offset:36864
	ds_read_b128 v[198:201], v144 offset:37888
	ds_read_b128 v[202:205], v144 offset:38912
	ds_read_b128 v[210:213], v144 offset:39936
	s_waitcnt vmcnt(8)
	s_waitcnt lgkmcnt(0)
	s_barrier
	s_setprio 1
	s_waitcnt lgkmcnt(0)
	v_mfma_f32_16x16x32_bf16 v[128:131], v[146:149], v[178:181], v[128:131]
	v_mfma_f32_16x16x32_bf16 v[124:127], v[154:157], v[178:181], v[124:127]
	v_mfma_f32_16x16x32_bf16 v[120:123], v[146:149], v[186:189], v[120:123]
	v_mfma_f32_16x16x32_bf16 v[116:119], v[154:157], v[186:189], v[116:119]
	v_mfma_f32_16x16x32_bf16 v[104:107], v[146:149], v[194:197], v[104:107]
	v_mfma_f32_16x16x32_bf16 v[100:103], v[154:157], v[194:197], v[100:103]
	v_mfma_f32_16x16x32_bf16 v[88:91], v[146:149], v[202:205], v[88:91]
	v_mfma_f32_16x16x32_bf16 v[84:87], v[154:157], v[202:205], v[84:87]
	v_mfma_f32_16x16x32_bf16 v[128:131], v[150:153], v[182:185], v[128:131]
	v_mfma_f32_16x16x32_bf16 v[124:127], v[158:161], v[182:185], v[124:127]
	v_mfma_f32_16x16x32_bf16 v[120:123], v[150:153], v[190:193], v[120:123]
	v_mfma_f32_16x16x32_bf16 v[116:119], v[158:161], v[190:193], v[116:119]
	v_mfma_f32_16x16x32_bf16 v[104:107], v[150:153], v[198:201], v[104:107]
	v_mfma_f32_16x16x32_bf16 v[100:103], v[158:161], v[198:201], v[100:103]
	v_mfma_f32_16x16x32_bf16 v[88:91], v[150:153], v[210:213], v[88:91]
	v_mfma_f32_16x16x32_bf16 v[84:87], v[158:161], v[210:213], v[84:87]
	v_mfma_f32_16x16x32_bf16 v[112:115], v[162:165], v[178:181], v[112:115]
	v_mfma_f32_16x16x32_bf16 v[108:111], v[170:173], v[178:181], v[108:111]
	v_mfma_f32_16x16x32_bf16 v[96:99], v[162:165], v[186:189], v[96:99]
	v_mfma_f32_16x16x32_bf16 v[92:95], v[170:173], v[186:189], v[92:95]
	v_mfma_f32_16x16x32_bf16 v[80:83], v[162:165], v[194:197], v[80:83]
	v_mfma_f32_16x16x32_bf16 v[76:79], v[170:173], v[194:197], v[76:79]
	v_mfma_f32_16x16x32_bf16 v[72:75], v[162:165], v[202:205], v[72:75]
	v_mfma_f32_16x16x32_bf16 v[68:71], v[170:173], v[202:205], v[68:71]
	v_mfma_f32_16x16x32_bf16 v[112:115], v[166:169], v[182:185], v[112:115]
	v_mfma_f32_16x16x32_bf16 v[108:111], v[174:177], v[182:185], v[108:111]
	v_mfma_f32_16x16x32_bf16 v[96:99], v[166:169], v[190:193], v[96:99]
	v_mfma_f32_16x16x32_bf16 v[92:95], v[174:177], v[190:193], v[92:95]
	v_mfma_f32_16x16x32_bf16 v[80:83], v[166:169], v[198:201], v[80:83]
	v_mfma_f32_16x16x32_bf16 v[76:79], v[174:177], v[198:201], v[76:79]
	v_mfma_f32_16x16x32_bf16 v[72:75], v[166:169], v[210:213], v[72:75]
	v_mfma_f32_16x16x32_bf16 v[68:71], v[174:177], v[210:213], v[68:71]
	s_setprio 0
	s_barrier
	s_add_i32 s54, s97, s16
	s_mov_b32 m0, s54
	s_nop 0
	s_add_u32 s98, s84, 0x80
	s_addc_u32 s99, s85, 0
	s_nop 0
	global_load_lds_dwordx4 v2, s[98:99]
	s_add_i32 m0, s54, 0x2000
	s_add_u32 s56, s84, 0x80080
	s_addc_u32 s57, s85, 0
	s_add_i32 s54, s48, s16
	global_load_lds_dwordx4 v136, s[98:99]
	s_mov_b32 m0, s54
	s_nop 0
	global_load_lds_dwordx4 v2, s[56:57]
	s_add_i32 m0, s54, 0x2000
	s_nop 0
	global_load_lds_dwordx4 v136, s[56:57]
	s_mov_b32 m0, s62
	s_nop 0
	s_add_u32 s98, s86, 0x80
	s_addc_u32 s99, s87, 0
	s_nop 0
	global_load_lds_dwordx4 v132, s[98:99]
	s_mov_b32 m0, s63
	s_nop 0
	global_load_lds_dwordx4 v134, s[98:99]
	ds_read_b128 v[178:181], v144 offset:49152
	ds_read_b128 v[182:185], v144 offset:50176
	ds_read_b128 v[186:189], v144 offset:51200
	ds_read_b128 v[190:193], v144 offset:52224
	ds_read_b128 v[194:197], v144 offset:53248
	ds_read_b128 v[198:201], v144 offset:54272
	ds_read_b128 v[202:205], v144 offset:55296
	ds_read_b128 v[210:213], v144 offset:56320
	s_waitcnt vmcnt(8)
	s_waitcnt lgkmcnt(0)
	s_barrier
	s_setprio 1
	s_waitcnt lgkmcnt(0)
	v_mfma_f32_16x16x32_bf16 v[64:67], v[146:149], v[178:181], v[64:67]
	v_mfma_f32_16x16x32_bf16 v[60:63], v[154:157], v[178:181], v[60:63]
	v_mfma_f32_16x16x32_bf16 v[56:59], v[146:149], v[186:189], v[56:59]
	v_mfma_f32_16x16x32_bf16 v[52:55], v[154:157], v[186:189], v[52:55]
	v_mfma_f32_16x16x32_bf16 v[40:43], v[146:149], v[194:197], v[40:43]
	v_mfma_f32_16x16x32_bf16 v[36:39], v[154:157], v[194:197], v[36:39]
	v_mfma_f32_16x16x32_bf16 v[24:27], v[146:149], v[202:205], v[24:27]
	v_mfma_f32_16x16x32_bf16 v[20:23], v[154:157], v[202:205], v[20:23]
	v_mfma_f32_16x16x32_bf16 v[64:67], v[150:153], v[182:185], v[64:67]
	v_mfma_f32_16x16x32_bf16 v[60:63], v[158:161], v[182:185], v[60:63]
	v_mfma_f32_16x16x32_bf16 v[56:59], v[150:153], v[190:193], v[56:59]
	v_mfma_f32_16x16x32_bf16 v[52:55], v[158:161], v[190:193], v[52:55]
	v_mfma_f32_16x16x32_bf16 v[40:43], v[150:153], v[198:201], v[40:43]
	v_mfma_f32_16x16x32_bf16 v[36:39], v[158:161], v[198:201], v[36:39]
	v_mfma_f32_16x16x32_bf16 v[24:27], v[150:153], v[210:213], v[24:27]
	v_mfma_f32_16x16x32_bf16 v[20:23], v[158:161], v[210:213], v[20:23]
	v_mfma_f32_16x16x32_bf16 v[48:51], v[162:165], v[178:181], v[48:51]
	v_mfma_f32_16x16x32_bf16 v[44:47], v[170:173], v[178:181], v[44:47]
	v_mfma_f32_16x16x32_bf16 v[32:35], v[162:165], v[186:189], v[32:35]
	v_mfma_f32_16x16x32_bf16 v[28:31], v[170:173], v[186:189], v[28:31]
	v_mfma_f32_16x16x32_bf16 v[16:19], v[162:165], v[194:197], v[16:19]
	v_mfma_f32_16x16x32_bf16 v[12:15], v[170:173], v[194:197], v[12:15]
	v_mfma_f32_16x16x32_bf16 v[8:11], v[162:165], v[202:205], v[8:11]
	v_mfma_f32_16x16x32_bf16 v[4:7], v[170:173], v[202:205], v[4:7]
	v_mfma_f32_16x16x32_bf16 v[48:51], v[166:169], v[182:185], v[48:51]
	v_mfma_f32_16x16x32_bf16 v[44:47], v[174:177], v[182:185], v[44:47]
	v_mfma_f32_16x16x32_bf16 v[32:35], v[166:169], v[190:193], v[32:35]
	v_mfma_f32_16x16x32_bf16 v[28:31], v[174:177], v[190:193], v[28:31]
	v_mfma_f32_16x16x32_bf16 v[16:19], v[166:169], v[198:201], v[16:19]
	v_mfma_f32_16x16x32_bf16 v[12:15], v[174:177], v[198:201], v[12:15]
	v_mfma_f32_16x16x32_bf16 v[8:11], v[166:169], v[210:213], v[8:11]
	v_mfma_f32_16x16x32_bf16 v[4:7], v[174:177], v[210:213], v[4:7]
	s_setprio 0
	s_barrier
	s_add_u32 s74, s74, 0x100
	s_addc_u32 s75, s75, 0
	s_add_u32 s23, s23, 0x100
	s_addc_u32 s35, s35, 0
	s_cmp_ge_u32 s55, s64
	s_mov_b32 s54, s55
	s_cbranch_scc0 .LBB0_521
	s_and_b64 vcc, exec, s[58:59]
	s_cbranch_vccz .LBB0_524
	s_barrier

.LBB0_694:
	s_add_u32 s57, s88, 0xfff80080
	s_addc_u32 s73, s89, -1
	s_add_i32 m0, s60, 0xc000
	s_add_i32 s75, s60, 0xe000
	global_load_lds_dwordx4 v138, s[88:89]
	s_mov_b32 m0, s75
	s_cmp_eq_u32 s56, 28
	global_load_lds_dwordx4 v140, s[88:89]
	s_cselect_b32 vcc_hi, s16, s73
	s_cselect_b32 vcc_lo, s17, s57
	s_cselect_b32 s91, s50, s55
	s_cselect_b32 s90, s51, s54
	ds_read_b128 v[148:151], v246
	ds_read_b128 v[152:155], v246 offset:1024
	ds_read_b128 v[156:159], v246 offset:2048
	ds_read_b128 v[160:163], v246 offset:3072
	ds_read_b128 v[164:167], v247
	ds_read_b128 v[168:171], v247 offset:1024
	ds_read_b128 v[172:175], v247 offset:2048
	ds_read_b128 v[176:179], v247 offset:3072
	ds_read_b128 v[180:183], v146
	ds_read_b128 v[184:187], v146 offset:1024
	ds_read_b128 v[188:191], v146 offset:2048
	ds_read_b128 v[192:195], v146 offset:3072
	ds_read_b128 v[196:199], v146 offset:4096
	ds_read_b128 v[200:203], v146 offset:5120
	ds_read_b128 v[210:213], v146 offset:6144
	ds_read_b128 v[214:217], v146 offset:7168
	s_waitcnt vmcnt(8)
	s_waitcnt lgkmcnt(0)
	s_barrier
	s_setprio 1
	s_waitcnt lgkmcnt(0)
	v_mfma_f32_16x16x32_bf16 v[128:131], v[148:151], v[180:183], v[128:131]
	v_mfma_f32_16x16x32_bf16 v[124:127], v[156:159], v[180:183], v[124:127]
	v_mfma_f32_16x16x32_bf16 v[112:115], v[148:151], v[188:191], v[112:115]
	v_mfma_f32_16x16x32_bf16 v[108:111], v[156:159], v[188:191], v[108:111]
	v_mfma_f32_16x16x32_bf16 v[96:99], v[148:151], v[196:199], v[96:99]
	v_mfma_f32_16x16x32_bf16 v[92:95], v[156:159], v[196:199], v[92:95]
	v_mfma_f32_16x16x32_bf16 v[80:83], v[148:151], v[210:213], v[80:83]
	v_mfma_f32_16x16x32_bf16 v[76:79], v[156:159], v[210:213], v[76:79]
	v_mfma_f32_16x16x32_bf16 v[128:131], v[152:155], v[184:187], v[128:131]
	v_mfma_f32_16x16x32_bf16 v[124:127], v[160:163], v[184:187], v[124:127]
	v_mfma_f32_16x16x32_bf16 v[112:115], v[152:155], v[192:195], v[112:115]
	v_mfma_f32_16x16x32_bf16 v[108:111], v[160:163], v[192:195], v[108:111]
	v_mfma_f32_16x16x32_bf16 v[96:99], v[152:155], v[200:203], v[96:99]
	v_mfma_f32_16x16x32_bf16 v[92:95], v[160:163], v[200:203], v[92:95]
	v_mfma_f32_16x16x32_bf16 v[80:83], v[152:155], v[214:217], v[80:83]
	v_mfma_f32_16x16x32_bf16 v[76:79], v[160:163], v[214:217], v[76:79]
	v_mfma_f32_16x16x32_bf16 v[120:123], v[164:167], v[180:183], v[120:123]
	v_mfma_f32_16x16x32_bf16 v[116:119], v[172:175], v[180:183], v[116:119]
	v_mfma_f32_16x16x32_bf16 v[104:107], v[164:167], v[188:191], v[104:107]
	v_mfma_f32_16x16x32_bf16 v[100:103], v[172:175], v[188:191], v[100:103]
	v_mfma_f32_16x16x32_bf16 v[88:91], v[164:167], v[196:199], v[88:91]
	v_mfma_f32_16x16x32_bf16 v[84:87], v[172:175], v[196:199], v[84:87]
	v_mfma_f32_16x16x32_bf16 v[72:75], v[164:167], v[210:213], v[72:75]
	v_mfma_f32_16x16x32_bf16 v[68:71], v[172:175], v[210:213], v[68:71]
	v_mfma_f32_16x16x32_bf16 v[120:123], v[168:171], v[184:187], v[120:123]
	v_mfma_f32_16x16x32_bf16 v[116:119], v[176:179], v[184:187], v[116:119]
	v_mfma_f32_16x16x32_bf16 v[104:107], v[168:171], v[192:195], v[104:107]
	v_mfma_f32_16x16x32_bf16 v[100:103], v[176:179], v[192:195], v[100:103]
	v_mfma_f32_16x16x32_bf16 v[88:91], v[168:171], v[200:203], v[88:91]
	v_mfma_f32_16x16x32_bf16 v[84:87], v[176:179], v[200:203], v[84:87]
	v_mfma_f32_16x16x32_bf16 v[72:75], v[168:171], v[214:217], v[72:75]
	v_mfma_f32_16x16x32_bf16 v[68:71], v[176:179], v[214:217], v[68:71]
	s_setprio 0
	s_barrier
	s_add_i32 s57, s33, s35
	s_mov_b32 m0, s57
	s_nop 0
	global_load_lds_dwordx4 v2, s[90:91]
	s_add_i32 m0, s57, 0x2000
	s_add_u32 s76, s90, 0x80000
	s_addc_u32 s77, s91, 0
	s_add_i32 s57, s96, s35
	global_load_lds_dwordx4 v132, s[90:91]
	s_mov_b32 m0, s57
	s_nop 0
	global_load_lds_dwordx4 v2, s[76:77]
	s_add_i32 m0, s57, 0x2000
	s_nop 0
	global_load_lds_dwordx4 v132, s[76:77]
	s_mov_b32 m0, s60
	s_nop 0
	global_load_lds_dwordx4 v136, vcc
	s_mov_b32 m0, s61
	s_nop 0
	global_load_lds_dwordx4 v134, vcc
	ds_read_b128 v[180:183], v146 offset:16384
	ds_read_b128 v[184:187], v146 offset:17408
	ds_read_b128 v[188:191], v146 offset:18432
	ds_read_b128 v[192:195], v146 offset:19456
	ds_read_b128 v[196:199], v146 offset:20480
	ds_read_b128 v[200:203], v146 offset:21504
	ds_read_b128 v[210:213], v146 offset:22528
	ds_read_b128 v[214:217], v146 offset:23552
	s_waitcnt vmcnt(8)
	s_waitcnt lgkmcnt(0)
	s_barrier
	s_setprio 1
	s_waitcnt lgkmcnt(0)
	v_mfma_f32_16x16x32_bf16 v[64:67], v[148:151], v[180:183], v[64:67]
	v_mfma_f32_16x16x32_bf16 v[60:63], v[156:159], v[180:183], v[60:63]
	v_mfma_f32_16x16x32_bf16 v[48:51], v[148:151], v[188:191], v[48:51]
	v_mfma_f32_16x16x32_bf16 v[44:47], v[156:159], v[188:191], v[44:47]
	v_mfma_f32_16x16x32_bf16 v[32:35], v[148:151], v[196:199], v[32:35]
	v_mfma_f32_16x16x32_bf16 v[28:31], v[156:159], v[196:199], v[28:31]
	v_mfma_f32_16x16x32_bf16 v[16:19], v[148:151], v[210:213], v[16:19]
	v_mfma_f32_16x16x32_bf16 v[12:15], v[156:159], v[210:213], v[12:15]
	v_mfma_f32_16x16x32_bf16 v[64:67], v[152:155], v[184:187], v[64:67]
	v_mfma_f32_16x16x32_bf16 v[60:63], v[160:163], v[184:187], v[60:63]
	v_mfma_f32_16x16x32_bf16 v[48:51], v[152:155], v[192:195], v[48:51]
	v_mfma_f32_16x16x32_bf16 v[44:47], v[160:163], v[192:195], v[44:47]
	v_mfma_f32_16x16x32_bf16 v[32:35], v[152:155], v[200:203], v[32:35]
	v_mfma_f32_16x16x32_bf16 v[28:31], v[160:163], v[200:203], v[28:31]
	v_mfma_f32_16x16x32_bf16 v[16:19], v[152:155], v[214:217], v[16:19]
	v_mfma_f32_16x16x32_bf16 v[12:15], v[160:163], v[214:217], v[12:15]
	v_mfma_f32_16x16x32_bf16 v[56:59], v[164:167], v[180:183], v[56:59]
	v_mfma_f32_16x16x32_bf16 v[52:55], v[172:175], v[180:183], v[52:55]
	v_mfma_f32_16x16x32_bf16 v[40:43], v[164:167], v[188:191], v[40:43]
	v_mfma_f32_16x16x32_bf16 v[36:39], v[172:175], v[188:191], v[36:39]
	v_mfma_f32_16x16x32_bf16 v[24:27], v[164:167], v[196:199], v[24:27]
	v_mfma_f32_16x16x32_bf16 v[20:23], v[172:175], v[196:199], v[20:23]
	v_mfma_f32_16x16x32_bf16 v[8:11], v[164:167], v[210:213], v[8:11]
	v_mfma_f32_16x16x32_bf16 v[4:7], v[172:175], v[210:213], v[4:7]
	v_mfma_f32_16x16x32_bf16 v[56:59], v[168:171], v[184:187], v[56:59]
	v_mfma_f32_16x16x32_bf16 v[52:55], v[176:179], v[184:187], v[52:55]
	v_mfma_f32_16x16x32_bf16 v[40:43], v[168:171], v[192:195], v[40:43]
	v_mfma_f32_16x16x32_bf16 v[36:39], v[176:179], v[192:195], v[36:39]
	v_mfma_f32_16x16x32_bf16 v[24:27], v[168:171], v[200:203], v[24:27]
	v_mfma_f32_16x16x32_bf16 v[20:23], v[176:179], v[200:203], v[20:23]
	v_mfma_f32_16x16x32_bf16 v[8:11], v[168:171], v[214:217], v[8:11]
	v_mfma_f32_16x16x32_bf16 v[4:7], v[176:179], v[214:217], v[4:7]
	s_setprio 0
	s_barrier
	s_add_u32 s76, vcc_lo, 0x80000
	s_addc_u32 s77, vcc_hi, 0
	s_mov_b32 m0, s62
	s_nop 0
	global_load_lds_dwordx4 v136, s[76:77]
	s_mov_b32 m0, s63
	s_nop 0
	global_load_lds_dwordx4 v134, s[76:77]
	ds_read_b128 v[148:151], v248
	ds_read_b128 v[152:155], v248 offset:1024
	ds_read_b128 v[156:159], v248 offset:2048
	ds_read_b128 v[160:163], v248 offset:3072
	ds_read_b128 v[164:167], v249
	ds_read_b128 v[168:171], v249 offset:1024
	ds_read_b128 v[172:175], v249 offset:2048
	ds_read_b128 v[176:179], v249 offset:3072
	ds_read_b128 v[180:183], v146 offset:32768
	ds_read_b128 v[184:187], v146 offset:33792
	ds_read_b128 v[188:191], v146 offset:34816
	ds_read_b128 v[192:195], v146 offset:35840
	ds_read_b128 v[196:199], v146 offset:36864
	ds_read_b128 v[200:203], v146 offset:37888
	ds_read_b128 v[210:213], v146 offset:38912
	ds_read_b128 v[214:217], v146 offset:39936
	s_waitcnt vmcnt(8)
	s_waitcnt lgkmcnt(0)
	s_barrier
	s_setprio 1
	s_waitcnt lgkmcnt(0)
	v_mfma_f32_16x16x32_bf16 v[128:131], v[148:151], v[180:183], v[128:131]
	v_mfma_f32_16x16x32_bf16 v[124:127], v[156:159], v[180:183], v[124:127]
	v_mfma_f32_16x16x32_bf16 v[112:115], v[148:151], v[188:191], v[112:115]
	v_mfma_f32_16x16x32_bf16 v[108:111], v[156:159], v[188:191], v[108:111]
	v_mfma_f32_16x16x32_bf16 v[96:99], v[148:151], v[196:199], v[96:99]
	v_mfma_f32_16x16x32_bf16 v[92:95], v[156:159], v[196:199], v[92:95]
	v_mfma_f32_16x16x32_bf16 v[80:83], v[148:151], v[210:213], v[80:83]
	v_mfma_f32_16x16x32_bf16 v[76:79], v[156:159], v[210:213], v[76:79]
	v_mfma_f32_16x16x32_bf16 v[128:131], v[152:155], v[184:187], v[128:131]
	v_mfma_f32_16x16x32_bf16 v[124:127], v[160:163], v[184:187], v[124:127]
	v_mfma_f32_16x16x32_bf16 v[112:115], v[152:155], v[192:195], v[112:115]
	v_mfma_f32_16x16x32_bf16 v[108:111], v[160:163], v[192:195], v[108:111]
	v_mfma_f32_16x16x32_bf16 v[96:99], v[152:155], v[200:203], v[96:99]
	v_mfma_f32_16x16x32_bf16 v[92:95], v[160:163], v[200:203], v[92:95]
	v_mfma_f32_16x16x32_bf16 v[80:83], v[152:155], v[214:217], v[80:83]
	v_mfma_f32_16x16x32_bf16 v[76:79], v[160:163], v[214:217], v[76:79]
	v_mfma_f32_16x16x32_bf16 v[120:123], v[164:167], v[180:183], v[120:123]
	v_mfma_f32_16x16x32_bf16 v[116:119], v[172:175], v[180:183], v[116:119]
	v_mfma_f32_16x16x32_bf16 v[104:107], v[164:167], v[188:191], v[104:107]
	v_mfma_f32_16x16x32_bf16 v[100:103], v[172:175], v[188:191], v[100:103]
	v_mfma_f32_16x16x32_bf16 v[88:91], v[164:167], v[196:199], v[88:91]
	v_mfma_f32_16x16x32_bf16 v[84:87], v[172:175], v[196:199], v[84:87]
	v_mfma_f32_16x16x32_bf16 v[72:75], v[164:167], v[210:213], v[72:75]
	v_mfma_f32_16x16x32_bf16 v[68:71], v[172:175], v[210:213], v[68:71]
	v_mfma_f32_16x16x32_bf16 v[120:123], v[168:171], v[184:187], v[120:123]
	v_mfma_f32_16x16x32_bf16 v[116:119], v[176:179], v[184:187], v[116:119]
	v_mfma_f32_16x16x32_bf16 v[104:107], v[168:171], v[192:195], v[104:107]
	v_mfma_f32_16x16x32_bf16 v[100:103], v[176:179], v[192:195], v[100:103]
	v_mfma_f32_16x16x32_bf16 v[88:91], v[168:171], v[200:203], v[88:91]
	v_mfma_f32_16x16x32_bf16 v[84:87], v[176:179], v[200:203], v[84:87]
	v_mfma_f32_16x16x32_bf16 v[72:75], v[168:171], v[214:217], v[72:75]
	v_mfma_f32_16x16x32_bf16 v[68:71], v[176:179], v[214:217], v[68:71]
	s_setprio 0
	s_barrier
	s_add_i32 s57, s97, s35
	s_mov_b32 m0, s57
	s_nop 0
	s_add_u32 s98, s90, 0x80
	s_addc_u32 s99, s91, 0
	s_nop 0
	global_load_lds_dwordx4 v2, s[98:99]
	s_add_i32 m0, s57, 0x2000
	s_add_u32 s76, s90, 0x80080
	s_addc_u32 s77, s91, 0
	s_add_i32 s57, s48, s35
	global_load_lds_dwordx4 v132, s[98:99]
	s_mov_b32 m0, s57
	s_nop 0
	global_load_lds_dwordx4 v2, s[76:77]
	s_add_i32 m0, s57, 0x2000
	s_nop 0
	global_load_lds_dwordx4 v132, s[76:77]
	s_mov_b32 m0, s64
	s_nop 0
	s_add_u32 s98, vcc_lo, 0x80
	s_addc_u32 s99, vcc_hi, 0
	s_nop 0
	global_load_lds_dwordx4 v136, s[98:99]
	s_mov_b32 m0, s58
	s_nop 0
	global_load_lds_dwordx4 v134, s[98:99]
	ds_read_b128 v[180:183], v146 offset:49152
	ds_read_b128 v[184:187], v146 offset:50176
	ds_read_b128 v[188:191], v146 offset:51200
	ds_read_b128 v[192:195], v146 offset:52224
	ds_read_b128 v[196:199], v146 offset:53248
	ds_read_b128 v[200:203], v146 offset:54272
	ds_read_b128 v[210:213], v146 offset:55296
	ds_read_b128 v[214:217], v146 offset:56320
	s_waitcnt vmcnt(8)
	s_waitcnt lgkmcnt(0)
	s_barrier
	s_setprio 1
	s_waitcnt lgkmcnt(0)
	v_mfma_f32_16x16x32_bf16 v[64:67], v[148:151], v[180:183], v[64:67]
	v_mfma_f32_16x16x32_bf16 v[60:63], v[156:159], v[180:183], v[60:63]
	v_mfma_f32_16x16x32_bf16 v[48:51], v[148:151], v[188:191], v[48:51]
	v_mfma_f32_16x16x32_bf16 v[44:47], v[156:159], v[188:191], v[44:47]
	v_mfma_f32_16x16x32_bf16 v[32:35], v[148:151], v[196:199], v[32:35]
	v_mfma_f32_16x16x32_bf16 v[28:31], v[156:159], v[196:199], v[28:31]
	v_mfma_f32_16x16x32_bf16 v[16:19], v[148:151], v[210:213], v[16:19]
	v_mfma_f32_16x16x32_bf16 v[12:15], v[156:159], v[210:213], v[12:15]
	v_mfma_f32_16x16x32_bf16 v[64:67], v[152:155], v[184:187], v[64:67]
	v_mfma_f32_16x16x32_bf16 v[60:63], v[160:163], v[184:187], v[60:63]
	v_mfma_f32_16x16x32_bf16 v[48:51], v[152:155], v[192:195], v[48:51]
	v_mfma_f32_16x16x32_bf16 v[44:47], v[160:163], v[192:195], v[44:47]
	v_mfma_f32_16x16x32_bf16 v[32:35], v[152:155], v[200:203], v[32:35]
	v_mfma_f32_16x16x32_bf16 v[28:31], v[160:163], v[200:203], v[28:31]
	v_mfma_f32_16x16x32_bf16 v[16:19], v[152:155], v[214:217], v[16:19]
	v_mfma_f32_16x16x32_bf16 v[12:15], v[160:163], v[214:217], v[12:15]
	v_mfma_f32_16x16x32_bf16 v[56:59], v[164:167], v[180:183], v[56:59]
	v_mfma_f32_16x16x32_bf16 v[52:55], v[172:175], v[180:183], v[52:55]
	v_mfma_f32_16x16x32_bf16 v[40:43], v[164:167], v[188:191], v[40:43]
	v_mfma_f32_16x16x32_bf16 v[36:39], v[172:175], v[188:191], v[36:39]
	v_mfma_f32_16x16x32_bf16 v[24:27], v[164:167], v[196:199], v[24:27]
	v_mfma_f32_16x16x32_bf16 v[20:23], v[172:175], v[196:199], v[20:23]
	v_mfma_f32_16x16x32_bf16 v[8:11], v[164:167], v[210:213], v[8:11]
	v_mfma_f32_16x16x32_bf16 v[4:7], v[172:175], v[210:213], v[4:7]
	v_mfma_f32_16x16x32_bf16 v[56:59], v[168:171], v[184:187], v[56:59]
	v_mfma_f32_16x16x32_bf16 v[52:55], v[176:179], v[184:187], v[52:55]
	v_mfma_f32_16x16x32_bf16 v[40:43], v[168:171], v[192:195], v[40:43]
	v_mfma_f32_16x16x32_bf16 v[36:39], v[176:179], v[192:195], v[36:39]
	v_mfma_f32_16x16x32_bf16 v[24:27], v[168:171], v[200:203], v[24:27]
	v_mfma_f32_16x16x32_bf16 v[20:23], v[176:179], v[200:203], v[20:23]
	v_mfma_f32_16x16x32_bf16 v[8:11], v[168:171], v[214:217], v[8:11]
	v_mfma_f32_16x16x32_bf16 v[4:7], v[176:179], v[214:217], v[4:7]
	s_setprio 0
	s_barrier
	s_add_i32 s56, s56, 2
	s_add_u32 s88, s88, 0x100
	s_addc_u32 s89, s89, 0
	s_add_u32 s54, s54, 0x100
	s_addc_u32 s55, s55, 0
	s_cmp_gt_u32 s56, 29
	s_cbranch_scc0 .LBB0_694
	s_and_b64 vcc, exec, s[68:69]
	s_cbranch_vccz .LBB0_697
	s_barrier

.LBB0_763:
	s_add_i32 s56, s55, 2
	s_add_u32 s57, s84, 0xffe00080
	s_addc_u32 s62, s85, -1
	s_add_i32 m0, s16, 0xc000
	s_add_i32 s63, s16, 0xe000
	global_load_lds_dwordx4 v138, s[84:85]
	s_mov_b32 m0, s63
	s_cmp_eq_u32 s23, s55
	global_load_lds_dwordx4 v140, s[84:85]
	s_cselect_b32 s89, s73, s62
	s_cselect_b32 s88, s72, s57
	s_cselect_b32 s87, s75, s35
	s_cselect_b32 s86, s74, s29
	ds_read_b128 v[146:149], v246
	ds_read_b128 v[150:153], v246 offset:1024
	ds_read_b128 v[154:157], v246 offset:2048
	ds_read_b128 v[158:161], v246 offset:3072
	ds_read_b128 v[162:165], v247
	ds_read_b128 v[166:169], v247 offset:1024
	ds_read_b128 v[170:173], v247 offset:2048
	ds_read_b128 v[174:177], v247 offset:3072
	ds_read_b128 v[178:181], v144
	ds_read_b128 v[182:185], v144 offset:1024
	ds_read_b128 v[186:189], v144 offset:2048
	ds_read_b128 v[190:193], v144 offset:3072
	ds_read_b128 v[194:197], v144 offset:4096
	ds_read_b128 v[198:201], v144 offset:5120
	ds_read_b128 v[202:205], v144 offset:6144
	ds_read_b128 v[210:213], v144 offset:7168
	s_waitcnt vmcnt(8)
	s_waitcnt lgkmcnt(0)
	s_barrier
	s_setprio 1
	s_waitcnt lgkmcnt(0)
	v_mfma_f32_16x16x32_bf16 v[128:131], v[146:149], v[178:181], v[128:131]
	v_mfma_f32_16x16x32_bf16 v[124:127], v[154:157], v[178:181], v[124:127]
	v_mfma_f32_16x16x32_bf16 v[120:123], v[146:149], v[186:189], v[120:123]
	v_mfma_f32_16x16x32_bf16 v[116:119], v[154:157], v[186:189], v[116:119]
	v_mfma_f32_16x16x32_bf16 v[104:107], v[146:149], v[194:197], v[104:107]
	v_mfma_f32_16x16x32_bf16 v[100:103], v[154:157], v[194:197], v[100:103]
	v_mfma_f32_16x16x32_bf16 v[88:91], v[146:149], v[202:205], v[88:91]
	v_mfma_f32_16x16x32_bf16 v[84:87], v[154:157], v[202:205], v[84:87]
	v_mfma_f32_16x16x32_bf16 v[128:131], v[150:153], v[182:185], v[128:131]
	v_mfma_f32_16x16x32_bf16 v[124:127], v[158:161], v[182:185], v[124:127]
	v_mfma_f32_16x16x32_bf16 v[120:123], v[150:153], v[190:193], v[120:123]
	v_mfma_f32_16x16x32_bf16 v[116:119], v[158:161], v[190:193], v[116:119]
	v_mfma_f32_16x16x32_bf16 v[104:107], v[150:153], v[198:201], v[104:107]
	v_mfma_f32_16x16x32_bf16 v[100:103], v[158:161], v[198:201], v[100:103]
	v_mfma_f32_16x16x32_bf16 v[88:91], v[150:153], v[210:213], v[88:91]
	v_mfma_f32_16x16x32_bf16 v[84:87], v[158:161], v[210:213], v[84:87]
	v_mfma_f32_16x16x32_bf16 v[112:115], v[162:165], v[178:181], v[112:115]
	v_mfma_f32_16x16x32_bf16 v[108:111], v[170:173], v[178:181], v[108:111]
	v_mfma_f32_16x16x32_bf16 v[96:99], v[162:165], v[186:189], v[96:99]
	v_mfma_f32_16x16x32_bf16 v[92:95], v[170:173], v[186:189], v[92:95]
	v_mfma_f32_16x16x32_bf16 v[80:83], v[162:165], v[194:197], v[80:83]
	v_mfma_f32_16x16x32_bf16 v[76:79], v[170:173], v[194:197], v[76:79]
	v_mfma_f32_16x16x32_bf16 v[72:75], v[162:165], v[202:205], v[72:75]
	v_mfma_f32_16x16x32_bf16 v[68:71], v[170:173], v[202:205], v[68:71]
	v_mfma_f32_16x16x32_bf16 v[112:115], v[166:169], v[182:185], v[112:115]
	v_mfma_f32_16x16x32_bf16 v[108:111], v[174:177], v[182:185], v[108:111]
	v_mfma_f32_16x16x32_bf16 v[96:99], v[166:169], v[190:193], v[96:99]
	v_mfma_f32_16x16x32_bf16 v[92:95], v[174:177], v[190:193], v[92:95]
	v_mfma_f32_16x16x32_bf16 v[80:83], v[166:169], v[198:201], v[80:83]
	v_mfma_f32_16x16x32_bf16 v[76:79], v[174:177], v[198:201], v[76:79]
	v_mfma_f32_16x16x32_bf16 v[72:75], v[166:169], v[210:213], v[72:75]
	v_mfma_f32_16x16x32_bf16 v[68:71], v[174:177], v[210:213], v[68:71]
	s_setprio 0
	s_barrier
	s_add_i32 s55, s33, s13
	s_mov_b32 m0, s55
	s_nop 0
	global_load_lds_dwordx4 v2, s[86:87]
	s_add_i32 m0, s55, 0x2000
	s_add_u32 s62, s86, 0x200000
	s_addc_u32 s63, s87, 0
	s_add_i32 s55, s96, s13
	global_load_lds_dwordx4 v136, s[86:87]
	s_mov_b32 m0, s55
	s_nop 0
	global_load_lds_dwordx4 v2, s[62:63]
	s_add_i32 m0, s55, 0x2000
	s_nop 0
	global_load_lds_dwordx4 v136, s[62:63]
	s_mov_b32 m0, s16
	s_nop 0
	global_load_lds_dwordx4 v132, s[88:89]
	s_mov_b32 m0, s17
	s_nop 0
	global_load_lds_dwordx4 v134, s[88:89]
	ds_read_b128 v[178:181], v144 offset:16384
	ds_read_b128 v[182:185], v144 offset:17408
	ds_read_b128 v[186:189], v144 offset:18432
	ds_read_b128 v[190:193], v144 offset:19456
	ds_read_b128 v[194:197], v144 offset:20480
	ds_read_b128 v[198:201], v144 offset:21504
	ds_read_b128 v[202:205], v144 offset:22528
	ds_read_b128 v[210:213], v144 offset:23552
	s_waitcnt vmcnt(8)
	s_waitcnt lgkmcnt(0)
	s_barrier
	s_setprio 1
	s_waitcnt lgkmcnt(0)
	v_mfma_f32_16x16x32_bf16 v[64:67], v[146:149], v[178:181], v[64:67]
	v_mfma_f32_16x16x32_bf16 v[60:63], v[154:157], v[178:181], v[60:63]
	v_mfma_f32_16x16x32_bf16 v[56:59], v[146:149], v[186:189], v[56:59]
	v_mfma_f32_16x16x32_bf16 v[52:55], v[154:157], v[186:189], v[52:55]
	v_mfma_f32_16x16x32_bf16 v[40:43], v[146:149], v[194:197], v[40:43]
	v_mfma_f32_16x16x32_bf16 v[36:39], v[154:157], v[194:197], v[36:39]
	v_mfma_f32_16x16x32_bf16 v[24:27], v[146:149], v[202:205], v[24:27]
	v_mfma_f32_16x16x32_bf16 v[20:23], v[154:157], v[202:205], v[20:23]
	v_mfma_f32_16x16x32_bf16 v[64:67], v[150:153], v[182:185], v[64:67]
	v_mfma_f32_16x16x32_bf16 v[60:63], v[158:161], v[182:185], v[60:63]
	v_mfma_f32_16x16x32_bf16 v[56:59], v[150:153], v[190:193], v[56:59]
	v_mfma_f32_16x16x32_bf16 v[52:55], v[158:161], v[190:193], v[52:55]
	v_mfma_f32_16x16x32_bf16 v[40:43], v[150:153], v[198:201], v[40:43]
	v_mfma_f32_16x16x32_bf16 v[36:39], v[158:161], v[198:201], v[36:39]
	v_mfma_f32_16x16x32_bf16 v[24:27], v[150:153], v[210:213], v[24:27]
	v_mfma_f32_16x16x32_bf16 v[20:23], v[158:161], v[210:213], v[20:23]
	v_mfma_f32_16x16x32_bf16 v[48:51], v[162:165], v[178:181], v[48:51]
	v_mfma_f32_16x16x32_bf16 v[44:47], v[170:173], v[178:181], v[44:47]
	v_mfma_f32_16x16x32_bf16 v[32:35], v[162:165], v[186:189], v[32:35]
	v_mfma_f32_16x16x32_bf16 v[28:31], v[170:173], v[186:189], v[28:31]
	v_mfma_f32_16x16x32_bf16 v[16:19], v[162:165], v[194:197], v[16:19]
	v_mfma_f32_16x16x32_bf16 v[12:15], v[170:173], v[194:197], v[12:15]
	v_mfma_f32_16x16x32_bf16 v[8:11], v[162:165], v[202:205], v[8:11]
	v_mfma_f32_16x16x32_bf16 v[4:7], v[170:173], v[202:205], v[4:7]
	v_mfma_f32_16x16x32_bf16 v[48:51], v[166:169], v[182:185], v[48:51]
	v_mfma_f32_16x16x32_bf16 v[44:47], v[174:177], v[182:185], v[44:47]
	v_mfma_f32_16x16x32_bf16 v[32:35], v[166:169], v[190:193], v[32:35]
	v_mfma_f32_16x16x32_bf16 v[28:31], v[174:177], v[190:193], v[28:31]
	v_mfma_f32_16x16x32_bf16 v[16:19], v[166:169], v[198:201], v[16:19]
	v_mfma_f32_16x16x32_bf16 v[12:15], v[174:177], v[198:201], v[12:15]
	v_mfma_f32_16x16x32_bf16 v[8:11], v[166:169], v[210:213], v[8:11]
	v_mfma_f32_16x16x32_bf16 v[4:7], v[174:177], v[210:213], v[4:7]
	s_setprio 0
	s_barrier
	s_add_u32 s62, s88, 0x200000
	s_addc_u32 s63, s89, 0
	s_mov_b32 m0, s58
	s_nop 0
	global_load_lds_dwordx4 v132, s[62:63]
	s_mov_b32 m0, s59
	s_nop 0
	global_load_lds_dwordx4 v134, s[62:63]
	ds_read_b128 v[146:149], v248
	ds_read_b128 v[150:153], v248 offset:1024
	ds_read_b128 v[154:157], v248 offset:2048
	ds_read_b128 v[158:161], v248 offset:3072
	ds_read_b128 v[162:165], v249
	ds_read_b128 v[166:169], v249 offset:1024
	ds_read_b128 v[170:173], v249 offset:2048
	ds_read_b128 v[174:177], v249 offset:3072
	ds_read_b128 v[178:181], v144 offset:32768
	ds_read_b128 v[182:185], v144 offset:33792
	ds_read_b128 v[186:189], v144 offset:34816
	ds_read_b128 v[190:193], v144 offset:35840
	ds_read_b128 v[194:197], v144 offset:36864
	ds_read_b128 v[198:201], v144 offset:37888
	ds_read_b128 v[202:205], v144 offset:38912
	ds_read_b128 v[210:213], v144 offset:39936
	s_waitcnt vmcnt(8)
	s_waitcnt lgkmcnt(0)
	s_barrier
	s_setprio 1
	s_waitcnt lgkmcnt(0)
	v_mfma_f32_16x16x32_bf16 v[128:131], v[146:149], v[178:181], v[128:131]
	v_mfma_f32_16x16x32_bf16 v[124:127], v[154:157], v[178:181], v[124:127]
	v_mfma_f32_16x16x32_bf16 v[120:123], v[146:149], v[186:189], v[120:123]
	v_mfma_f32_16x16x32_bf16 v[116:119], v[154:157], v[186:189], v[116:119]
	v_mfma_f32_16x16x32_bf16 v[104:107], v[146:149], v[194:197], v[104:107]
	v_mfma_f32_16x16x32_bf16 v[100:103], v[154:157], v[194:197], v[100:103]
	v_mfma_f32_16x16x32_bf16 v[88:91], v[146:149], v[202:205], v[88:91]
	v_mfma_f32_16x16x32_bf16 v[84:87], v[154:157], v[202:205], v[84:87]
	v_mfma_f32_16x16x32_bf16 v[128:131], v[150:153], v[182:185], v[128:131]
	v_mfma_f32_16x16x32_bf16 v[124:127], v[158:161], v[182:185], v[124:127]
	v_mfma_f32_16x16x32_bf16 v[120:123], v[150:153], v[190:193], v[120:123]
	v_mfma_f32_16x16x32_bf16 v[116:119], v[158:161], v[190:193], v[116:119]
	v_mfma_f32_16x16x32_bf16 v[104:107], v[150:153], v[198:201], v[104:107]
	v_mfma_f32_16x16x32_bf16 v[100:103], v[158:161], v[198:201], v[100:103]
	v_mfma_f32_16x16x32_bf16 v[88:91], v[150:153], v[210:213], v[88:91]
	v_mfma_f32_16x16x32_bf16 v[84:87], v[158:161], v[210:213], v[84:87]
	v_mfma_f32_16x16x32_bf16 v[112:115], v[162:165], v[178:181], v[112:115]
	v_mfma_f32_16x16x32_bf16 v[108:111], v[170:173], v[178:181], v[108:111]
	v_mfma_f32_16x16x32_bf16 v[96:99], v[162:165], v[186:189], v[96:99]
	v_mfma_f32_16x16x32_bf16 v[92:95], v[170:173], v[186:189], v[92:95]
	v_mfma_f32_16x16x32_bf16 v[80:83], v[162:165], v[194:197], v[80:83]
	v_mfma_f32_16x16x32_bf16 v[76:79], v[170:173], v[194:197], v[76:79]
	v_mfma_f32_16x16x32_bf16 v[72:75], v[162:165], v[202:205], v[72:75]
	v_mfma_f32_16x16x32_bf16 v[68:71], v[170:173], v[202:205], v[68:71]
	v_mfma_f32_16x16x32_bf16 v[112:115], v[166:169], v[182:185], v[112:115]
	v_mfma_f32_16x16x32_bf16 v[108:111], v[174:177], v[182:185], v[108:111]
	v_mfma_f32_16x16x32_bf16 v[96:99], v[166:169], v[190:193], v[96:99]
	v_mfma_f32_16x16x32_bf16 v[92:95], v[174:177], v[190:193], v[92:95]
	v_mfma_f32_16x16x32_bf16 v[80:83], v[166:169], v[198:201], v[80:83]
	v_mfma_f32_16x16x32_bf16 v[76:79], v[174:177], v[198:201], v[76:79]
	v_mfma_f32_16x16x32_bf16 v[72:75], v[166:169], v[210:213], v[72:75]
	v_mfma_f32_16x16x32_bf16 v[68:71], v[174:177], v[210:213], v[68:71]
	s_setprio 0
	s_barrier
	s_add_i32 s55, s97, s13
	s_mov_b32 m0, s55
	s_nop 0
	s_add_u32 s98, s86, 0x80
	s_addc_u32 s99, s87, 0
	s_nop 0
	global_load_lds_dwordx4 v2, s[98:99]
	s_add_i32 m0, s55, 0x2000
	s_add_u32 s62, s86, 0x200080
	s_addc_u32 s63, s87, 0
	s_add_i32 s55, s48, s13
	global_load_lds_dwordx4 v136, s[98:99]
	s_mov_b32 m0, s55
	s_nop 0
	global_load_lds_dwordx4 v2, s[62:63]
	s_add_i32 m0, s55, 0x2000
	s_nop 0
	global_load_lds_dwordx4 v136, s[62:63]
	s_mov_b32 m0, s60
	s_nop 0
	s_add_u32 s98, s88, 0x80
	s_addc_u32 s99, s89, 0
	s_nop 0
	global_load_lds_dwordx4 v132, s[98:99]
	s_mov_b32 m0, s61
	s_nop 0
	global_load_lds_dwordx4 v134, s[98:99]
	ds_read_b128 v[178:181], v144 offset:49152
	ds_read_b128 v[182:185], v144 offset:50176
	ds_read_b128 v[186:189], v144 offset:51200
	ds_read_b128 v[190:193], v144 offset:52224
	ds_read_b128 v[194:197], v144 offset:53248
	ds_read_b128 v[198:201], v144 offset:54272
	ds_read_b128 v[202:205], v144 offset:55296
	ds_read_b128 v[210:213], v144 offset:56320
	s_waitcnt vmcnt(8)
	s_waitcnt lgkmcnt(0)
	s_barrier
	s_setprio 1
	s_waitcnt lgkmcnt(0)
	v_mfma_f32_16x16x32_bf16 v[64:67], v[146:149], v[178:181], v[64:67]
	v_mfma_f32_16x16x32_bf16 v[60:63], v[154:157], v[178:181], v[60:63]
	v_mfma_f32_16x16x32_bf16 v[56:59], v[146:149], v[186:189], v[56:59]
	v_mfma_f32_16x16x32_bf16 v[52:55], v[154:157], v[186:189], v[52:55]
	v_mfma_f32_16x16x32_bf16 v[40:43], v[146:149], v[194:197], v[40:43]
	v_mfma_f32_16x16x32_bf16 v[36:39], v[154:157], v[194:197], v[36:39]
	v_mfma_f32_16x16x32_bf16 v[24:27], v[146:149], v[202:205], v[24:27]
	v_mfma_f32_16x16x32_bf16 v[20:23], v[154:157], v[202:205], v[20:23]
	v_mfma_f32_16x16x32_bf16 v[64:67], v[150:153], v[182:185], v[64:67]
	v_mfma_f32_16x16x32_bf16 v[60:63], v[158:161], v[182:185], v[60:63]
	v_mfma_f32_16x16x32_bf16 v[56:59], v[150:153], v[190:193], v[56:59]
	v_mfma_f32_16x16x32_bf16 v[52:55], v[158:161], v[190:193], v[52:55]
	v_mfma_f32_16x16x32_bf16 v[40:43], v[150:153], v[198:201], v[40:43]
	v_mfma_f32_16x16x32_bf16 v[36:39], v[158:161], v[198:201], v[36:39]
	v_mfma_f32_16x16x32_bf16 v[24:27], v[150:153], v[210:213], v[24:27]
	v_mfma_f32_16x16x32_bf16 v[20:23], v[158:161], v[210:213], v[20:23]
	v_mfma_f32_16x16x32_bf16 v[48:51], v[162:165], v[178:181], v[48:51]
	v_mfma_f32_16x16x32_bf16 v[44:47], v[170:173], v[178:181], v[44:47]
	v_mfma_f32_16x16x32_bf16 v[32:35], v[162:165], v[186:189], v[32:35]
	v_mfma_f32_16x16x32_bf16 v[28:31], v[170:173], v[186:189], v[28:31]
	v_mfma_f32_16x16x32_bf16 v[16:19], v[162:165], v[194:197], v[16:19]
	v_mfma_f32_16x16x32_bf16 v[12:15], v[170:173], v[194:197], v[12:15]
	v_mfma_f32_16x16x32_bf16 v[8:11], v[162:165], v[202:205], v[8:11]
	v_mfma_f32_16x16x32_bf16 v[4:7], v[170:173], v[202:205], v[4:7]
	v_mfma_f32_16x16x32_bf16 v[48:51], v[166:169], v[182:185], v[48:51]
	v_mfma_f32_16x16x32_bf16 v[44:47], v[174:177], v[182:185], v[44:47]
	v_mfma_f32_16x16x32_bf16 v[32:35], v[166:169], v[190:193], v[32:35]
	v_mfma_f32_16x16x32_bf16 v[28:31], v[174:177], v[190:193], v[28:31]
	v_mfma_f32_16x16x32_bf16 v[16:19], v[166:169], v[198:201], v[16:19]
	v_mfma_f32_16x16x32_bf16 v[12:15], v[174:177], v[198:201], v[12:15]
	v_mfma_f32_16x16x32_bf16 v[8:11], v[166:169], v[210:213], v[8:11]
	v_mfma_f32_16x16x32_bf16 v[4:7], v[174:177], v[210:213], v[4:7]
	s_setprio 0
	s_barrier
	s_add_u32 s84, s84, 0x100
	s_addc_u32 s85, s85, 0
	s_add_u32 s29, s29, 0x100
	s_addc_u32 s35, s35, 0
	s_cmp_ge_u32 s56, s51
	s_mov_b32 s55, s56
	s_cbranch_scc0 .LBB0_763
	s_and_b64 vcc, exec, s[68:69]
	s_cbranch_vccz .LBB0_766
	s_barrier
